# nt cache policy on streamed-once data: P1 x and f32 weight loads, P2 ACT stores; P3 epilogue loads pipelined; MLA loop role-split
# baseline (speedup 1.0000x reference)
; template <int MODE, bool XB> __device__ __forceinline__ void norm_pass(const void* __restrict__ X, const float* __restrict__ g, const float* __restrict__ shift, const float* __restrict__ scale, ...
;     ...
;     for (int m0 = gw * 16; m0 < M; m0 += NGW * 16) {
;         const int b = m0 / SEQ;
;         f32x4 gm[4], sh[4];
; #pragma unroll
;         for (int j = 0; j < 4; ++j) { const int col = 4 * lane + 256 * j; gm[j] = *(const f32x4*)(g + col);
;             if (MODE == 0) { gm[j] = gm[j] * (*(const f32x4*)(scale + (size_t)b * NMOD9 + col) + 1.0f); sh[j] = *(const f32x4*)(shift + (size_t)b * NMOD9 + col); } }
; #pragma unroll 4
;         for (int r = 0; r < 16; ++r) {
;             f32x4 v[4]; float s = 0.f;
; #pragma unroll
;             for (int j = 0; j < 4; ++j) {
;                 if constexpr (XB) { const v2u w = *(const v2u*)((const bf16*)X + (size_t)(m0 + r) * D + 4 * lane + 256 * j);
;                     v[j] = (f32x4){__uint_as_float(w.x << 16), __uint_as_float(w.x & 0xffff0000u), __uint_as_float(w.y << 16), __uint_as_float(w.y & 0xffff0000u)}; }
;                 else v[j] = *(const f32x4*)((const float*)X + (size_t)(m0 + r) * D + 4 * lane + 256 * j);
;                 s += (v[j][0] * v[j][0] + v[j][1] * v[j][1]) + (v[j][2] * v[j][2] + v[j][3] * v[j][3]); }
;             const float rstd = 1.0f / sqrtf(wave_sum(s) * (1.f / D) + 1e-6f);
.LBB0_51:
	s_add_i32 s0, s54, s38
	global_load_dwordx4 v[32:35], v[126:127], off offset:-2048 nt
	global_load_dwordx4 v[36:39], v[126:127], off offset:-1024 nt
	global_load_dwordx4 v[40:43], v[126:127], off nt
	global_load_dwordx4 v[44:47], v[126:127], off offset:1024 nt
	s_add_i32 s4, s0, 17
	s_add_i32 s6, s0, 18
	s_add_i32 s0, s0, 19
	s_ashr_i32 s5, s4, 31
	s_ashr_i32 s7, s6, 31
	s_ashr_i32 s1, s0, 31
	s_lshl_b64 s[10:11], s[4:5], 12
	s_lshl_b64 s[12:13], s[6:7], 12
	s_lshl_b64 s[14:15], s[0:1], 12
	v_lshl_add_u64 v[48:49], v[96:97], 0, s[10:11]
	v_lshl_add_u64 v[50:51], v[96:97], 0, s[12:13]
	v_lshl_add_u64 v[56:57], v[96:97], 0, s[14:15]
	global_load_dwordx4 v[92:95], v[48:49], off nt
	global_load_dwordx4 v[84:87], v[48:49], off offset:1024 nt
	global_load_dwordx4 v[80:83], v[48:49], off offset:3072 nt
	global_load_dwordx4 v[88:91], v[48:49], off offset:2048 nt
	global_load_dwordx4 v[76:79], v[50:51], off nt
	global_load_dwordx4 v[68:71], v[50:51], off offset:1024 nt
	global_load_dwordx4 v[64:67], v[50:51], off offset:3072 nt
	global_load_dwordx4 v[72:75], v[50:51], off offset:2048 nt
	global_load_dwordx4 v[60:63], v[56:57], off nt
	global_load_dwordx4 v[52:55], v[56:57], off offset:1024 nt
	s_nop 0
	global_load_dwordx4 v[48:51], v[56:57], off offset:3072 nt
	s_nop 0
	global_load_dwordx4 v[56:59], v[56:57], off offset:2048 nt
	s_lshl_b64 s[0:1], s[0:1], 11
	s_lshl_b64 s[4:5], s[4:5], 11
	s_lshl_b64 s[6:7], s[6:7], 11
	v_lshl_add_u64 v[128:129], v[98:99], 0, s[0:1]
	v_lshl_add_u64 v[132:133], v[98:99], 0, s[4:5]
	v_lshl_add_u64 v[130:131], v[98:99], 0, s[6:7]
	s_add_i32 s38, s38, 4
	v_lshl_add_u64 v[126:127], v[126:127], 0, s[74:75]
	s_cmp_lg_u32 s38, 0
	s_waitcnt vmcnt(15)
	v_pk_mul_f32 v[144:145], v[34:35], v[34:35]
	v_pk_mul_f32 v[146:147], v[32:33], v[32:33]
	s_waitcnt vmcnt(14)
	v_pk_mul_f32 v[148:149], v[38:39], v[38:39]
	v_pk_mul_f32 v[150:151], v[36:37], v[36:37]
	v_pk_mov_b32 v[156:157], v[146:147], v[144:145] op_sel:[1,0]
	v_mov_b32_e32 v147, v145
	v_pk_mov_b32 v[144:145], v[150:151], v[148:149] op_sel:[1,0]
	v_mov_b32_e32 v151, v149
	s_waitcnt vmcnt(12)
	v_mul_f32_e32 v155, v45, v45
	v_mul_f32_e32 v152, v41, v41
	v_mul_f32_e32 v154, v43, v43
	v_pk_add_f32 v[146:147], v[156:157], v[146:147]
	v_pk_add_f32 v[144:145], v[144:145], v[150:151]
	v_mul_f32_e32 v143, v44, v44
	v_mul_f32_e32 v158, v46, v46
	v_mul_f32_e32 v159, v47, v47
	v_pk_fma_f32 v[148:149], v[40:41], v[40:41], v[152:153] op_sel_hi:[1,1,0]
	v_pk_fma_f32 v[152:153], v[42:43], v[42:43], v[154:155] op_sel_hi:[1,1,0]
	v_pk_add_f32 v[146:147], v[146:147], v[146:147] op_sel:[0,1] op_sel_hi:[1,0]
	v_pk_add_f32 v[144:145], v[144:145], v[144:145] op_sel:[0,1] op_sel_hi:[1,0]
	v_mov_b32_e32 v149, v158
	v_mov_b32_e32 v153, v159
	v_mov_b32_e32 v147, v143
	v_mov_b32_e32 v145, v155
	v_pk_add_f32 v[148:149], v[148:149], v[152:153]
	v_pk_add_f32 v[144:145], v[146:147], v[144:145]
	s_waitcnt vmcnt(11)
	v_pk_mul_f32 v[146:147], v[94:95], v[94:95]
	v_pk_mul_f32 v[150:151], v[92:93], v[92:93]
	s_waitcnt vmcnt(10)
	v_pk_mul_f32 v[152:153], v[86:87], v[86:87]
	v_pk_mul_f32 v[154:155], v[84:85], v[84:85]
	s_waitcnt vmcnt(9)
	v_mul_f32_e32 v183, v81, v81
	s_waitcnt vmcnt(8)
	v_mul_f32_e32 v156, v89, v89
	v_mul_f32_e32 v158, v91, v91
	s_waitcnt vmcnt(7)
	v_pk_mul_f32 v[160:161], v[78:79], v[78:79]
	v_pk_mul_f32 v[162:163], v[76:77], v[76:77]
	s_waitcnt vmcnt(6)
	v_pk_mul_f32 v[164:165], v[70:71], v[70:71]
	v_pk_mul_f32 v[166:167], v[68:69], v[68:69]
	s_waitcnt vmcnt(4)
	v_mul_f32_e32 v168, v73, v73
	v_mul_f32_e32 v170, v75, v75
	s_waitcnt vmcnt(3)
	v_pk_mul_f32 v[172:173], v[62:63], v[62:63]
	v_pk_mul_f32 v[174:175], v[60:61], v[60:61]
	s_waitcnt vmcnt(2)
	v_pk_mul_f32 v[176:177], v[54:55], v[54:55]
	v_pk_mul_f32 v[178:179], v[52:53], v[52:53]
	s_waitcnt vmcnt(0)
	v_mul_f32_e32 v180, v57, v57
	v_mul_f32_e32 v182, v59, v59
	v_pk_add_f32 v[144:145], v[144:145], v[148:149]
	v_pk_mov_b32 v[148:149], v[150:151], v[146:147] op_sel:[1,0]
	v_mov_b32_e32 v151, v147
	v_pk_mov_b32 v[146:147], v[154:155], v[152:153] op_sel:[1,0]
	v_mov_b32_e32 v155, v153
	v_pk_fma_f32 v[152:153], v[88:89], v[88:89], v[156:157] op_sel_hi:[1,1,0]
	v_pk_fma_f32 v[156:157], v[90:91], v[90:91], v[158:159] op_sel_hi:[1,1,0]
	v_pk_mov_b32 v[158:159], v[162:163], v[160:161] op_sel:[1,0]
	v_mov_b32_e32 v163, v161
	v_pk_mov_b32 v[160:161], v[166:167], v[164:165] op_sel:[1,0]
	v_mov_b32_e32 v167, v165
	v_pk_fma_f32 v[164:165], v[72:73], v[72:73], v[168:169] op_sel_hi:[1,1,0]
	v_pk_fma_f32 v[168:169], v[74:75], v[74:75], v[170:171] op_sel_hi:[1,1,0]
	v_pk_mov_b32 v[170:171], v[174:175], v[172:173] op_sel:[1,0]
	v_mov_b32_e32 v175, v173
	v_pk_mov_b32 v[172:173], v[178:179], v[176:177] op_sel:[1,0]
	v_mov_b32_e32 v179, v177
	v_pk_fma_f32 v[176:177], v[56:57], v[56:57], v[180:181] op_sel_hi:[1,1,0]
	v_pk_fma_f32 v[180:181], v[58:59], v[58:59], v[182:183] op_sel_hi:[1,1,0]
	v_add_f32_e32 v182, v144, v145
	v_pk_add_f32 v[144:145], v[148:149], v[150:151]
	v_pk_add_f32 v[146:147], v[146:147], v[154:155]
	v_pk_add_f32 v[148:149], v[158:159], v[162:163]
	v_pk_add_f32 v[150:151], v[160:161], v[166:167]
	ds_bpermute_b32 v162, v134, v182
	v_mul_f32_e32 v143, v80, v80
	v_mul_f32_e32 v184, v82, v82
	v_mul_f32_e32 v185, v83, v83
	v_mul_f32_e32 v186, v64, v64
	v_mul_f32_e32 v187, v65, v65
	v_mul_f32_e32 v190, v66, v66
	v_mul_f32_e32 v191, v67, v67
	v_pk_add_f32 v[154:155], v[170:171], v[174:175]
	v_pk_add_f32 v[158:159], v[172:173], v[178:179]
	v_pk_add_f32 v[144:145], v[144:145], v[144:145] op_sel:[0,1] op_sel_hi:[1,0]
	v_pk_add_f32 v[146:147], v[146:147], v[146:147] op_sel:[0,1] op_sel_hi:[1,0]
	v_pk_add_f32 v[148:149], v[148:149], v[148:149] op_sel:[0,1] op_sel_hi:[1,0]
	v_pk_add_f32 v[150:151], v[150:151], v[150:151] op_sel:[0,1] op_sel_hi:[1,0]
	v_mul_f32_e32 v192, v48, v48
	v_mul_f32_e32 v193, v49, v49
	v_mul_f32_e32 v194, v50, v50
	v_mul_f32_e32 v195, v51, v51
	v_mov_b32_e32 v153, v184
	v_mov_b32_e32 v157, v185
	v_mov_b32_e32 v165, v190
	v_mov_b32_e32 v169, v191
	v_pk_add_f32 v[154:155], v[154:155], v[154:155] op_sel:[0,1] op_sel_hi:[1,0]
	v_pk_add_f32 v[158:159], v[158:159], v[158:159] op_sel:[0,1] op_sel_hi:[1,0]
	v_mov_b32_e32 v145, v143
	v_mov_b32_e32 v147, v183
	v_mov_b32_e32 v149, v186
	v_mov_b32_e32 v151, v187
	v_mov_b32_e32 v177, v194
	v_mov_b32_e32 v181, v195
	v_pk_add_f32 v[152:153], v[152:153], v[156:157]
	v_pk_add_f32 v[156:157], v[164:165], v[168:169]
	v_mov_b32_e32 v155, v192
	v_mov_b32_e32 v159, v193
	v_pk_add_f32 v[144:145], v[144:145], v[146:147]
	v_pk_add_f32 v[146:147], v[148:149], v[150:151]
	v_pk_add_f32 v[160:161], v[176:177], v[180:181]
	v_pk_add_f32 v[148:149], v[154:155], v[158:159]
	v_pk_add_f32 v[144:145], v[144:145], v[152:153]
	v_pk_add_f32 v[146:147], v[146:147], v[156:157]
	v_pk_add_f32 v[148:149], v[148:149], v[160:161]
	v_add_f32_e32 v143, v144, v145
	v_add_f32_e32 v144, v146, v147
	s_waitcnt lgkmcnt(0)
; __device__ __forceinline__ float wave_sum(float v) {
; #pragma unroll
;     for (int o = 1; o < 64; o <<= 1) v += __shfl_xor(v, o);
;     return v;
; }
; template <int MODE, bool XB> __device__ __forceinline__ void norm_pass(const void* __restrict__ X, const float* __restrict__ g, const float* __restrict__ shift, const float* __restrict__ scale, ...
;     ...
;             const float rstd = 1.0f / sqrtf(wave_sum(s) * (1.f / D) + 1e-6f);
	v_add_f32_e32 v146, v182, v162
	v_add_f32_e32 v145, v148, v149
	ds_bpermute_b32 v147, v134, v143
	ds_bpermute_b32 v150, v135, v146
	ds_bpermute_b32 v148, v134, v144
	ds_bpermute_b32 v149, v134, v145
	s_waitcnt lgkmcnt(3)
	v_add_f32_e32 v143, v143, v147
	s_waitcnt lgkmcnt(2)
	v_add_f32_e32 v146, v146, v150
	s_waitcnt lgkmcnt(1)
	v_add_f32_e32 v144, v144, v148
	s_waitcnt lgkmcnt(0)
	v_add_f32_e32 v145, v145, v149
	ds_bpermute_b32 v147, v135, v143
	ds_bpermute_b32 v150, v136, v146
	ds_bpermute_b32 v148, v135, v144
	ds_bpermute_b32 v149, v135, v145
	s_waitcnt lgkmcnt(3)
	v_add_f32_e32 v143, v143, v147
	s_waitcnt lgkmcnt(2)
	v_add_f32_e32 v146, v146, v150
	s_waitcnt lgkmcnt(1)
	v_add_f32_e32 v144, v144, v148
	s_waitcnt lgkmcnt(0)
	v_add_f32_e32 v145, v145, v149
	ds_bpermute_b32 v147, v136, v143
	ds_bpermute_b32 v150, v137, v146
	ds_bpermute_b32 v148, v136, v144
	ds_bpermute_b32 v149, v136, v145
	s_waitcnt lgkmcnt(3)
	v_add_f32_e32 v143, v143, v147
	s_waitcnt lgkmcnt(2)
	v_add_f32_e32 v146, v146, v150
	s_waitcnt lgkmcnt(1)
	v_add_f32_e32 v144, v144, v148
	s_waitcnt lgkmcnt(0)
	v_add_f32_e32 v145, v145, v149
	ds_bpermute_b32 v147, v137, v143
	ds_bpermute_b32 v150, v138, v146
	ds_bpermute_b32 v148, v137, v144
	ds_bpermute_b32 v149, v137, v145
	s_waitcnt lgkmcnt(3)
	v_add_f32_e32 v143, v143, v147
	s_waitcnt lgkmcnt(2)
	v_add_f32_e32 v146, v146, v150
	s_waitcnt lgkmcnt(1)
	v_add_f32_e32 v144, v144, v148
	s_waitcnt lgkmcnt(0)
	v_add_f32_e32 v145, v145, v149
	ds_bpermute_b32 v147, v138, v143
	ds_bpermute_b32 v150, v139, v146
	ds_bpermute_b32 v148, v138, v144
	ds_bpermute_b32 v149, v138, v145
	s_waitcnt lgkmcnt(3)
	v_add_f32_e32 v143, v143, v147
	s_waitcnt lgkmcnt(2)
	v_add_f32_e32 v146, v146, v150
	s_waitcnt lgkmcnt(1)
	v_add_f32_e32 v144, v144, v148
	s_waitcnt lgkmcnt(0)
	v_add_f32_e32 v145, v145, v149
	ds_bpermute_b32 v147, v139, v143
	v_fmamk_f32 v146, v146, 0x3a800000, v141
	ds_bpermute_b32 v148, v139, v144
	ds_bpermute_b32 v149, v139, v145
	v_mul_f32_e32 v150, 0x4f800000, v146
	v_cmp_gt_f32_e32 vcc, s33, v146
	s_waitcnt lgkmcnt(2)
	v_add_f32_e32 v143, v143, v147
	s_waitcnt lgkmcnt(1)
	v_add_f32_e32 v144, v144, v148
	v_cndmask_b32_e32 v146, v146, v150, vcc
	v_sqrt_f32_e32 v150, v146
	s_waitcnt lgkmcnt(0)
	v_add_f32_e32 v145, v145, v149
	v_fmamk_f32 v143, v143, 0x3a800000, v141
	v_fmamk_f32 v144, v144, 0x3a800000, v141
	v_fmamk_f32 v145, v145, 0x3a800000, v141
	v_mul_f32_e32 v147, 0x4f800000, v143
	v_cmp_gt_f32_e64 s[0:1], s33, v143
	v_add_u32_e32 v151, -1, v150
	v_mul_f32_e32 v148, 0x4f800000, v144
	v_cmp_gt_f32_e64 s[4:5], s33, v144
	v_mul_f32_e32 v149, 0x4f800000, v145
	v_cmp_gt_f32_e64 s[6:7], s33, v145
	v_add_u32_e32 v152, 1, v150
	v_cndmask_b32_e64 v143, v143, v147, s[0:1]
	v_fma_f32 v147, -v151, v150, v146
	v_cndmask_b32_e64 v144, v144, v148, s[4:5]
	v_cndmask_b32_e64 v145, v145, v149, s[6:7]
	v_fma_f32 v148, -v152, v150, v146
	v_cmp_ge_f32_e64 s[10:11], 0, v147
	v_sqrt_f32_e32 v149, v143
	v_sqrt_f32_e32 v154, v145
	v_cndmask_b32_e64 v147, v150, v151, s[10:11]
	v_cmp_lt_f32_e64 s[10:11], 0, v148
	v_sqrt_f32_e32 v153, v144
	v_add_u32_e32 v155, -1, v154
	v_cndmask_b32_e64 v147, v147, v152, s[10:11]
	v_mul_f32_e32 v148, 0x37800000, v147
	v_cndmask_b32_e32 v147, v147, v148, vcc
	v_cmp_class_f32_e32 vcc, v146, v142
	v_add_u32_e32 v148, -1, v149
	v_add_u32_e32 v150, 1, v149
	v_cndmask_b32_e32 v146, v147, v146, vcc
	v_add_u32_e32 v151, -1, v153
	v_add_u32_e32 v156, 1, v154
	v_fma_f32 v147, -v148, v149, v143
	v_fma_f32 v160, -v155, v154, v145
	v_div_scale_f32 v162, s[10:11], v146, v146, 1.0
	v_add_u32_e32 v152, 1, v153
	v_fma_f32 v157, -v150, v149, v143
	v_fma_f32 v158, -v151, v153, v144
	v_fma_f32 v161, -v156, v154, v145
	v_cmp_ge_f32_e64 s[10:11], 0, v147
	v_cmp_ge_f32_e64 s[14:15], 0, v160
	v_fma_f32 v159, -v152, v153, v144
	v_cndmask_b32_e64 v147, v149, v148, s[10:11]
	v_cmp_lt_f32_e64 s[10:11], 0, v157
	v_cmp_ge_f32_e64 s[12:13], 0, v158
	v_cndmask_b32_e64 v149, v154, v155, s[14:15]
	v_cmp_lt_f32_e64 s[14:15], 0, v161
	v_cndmask_b32_e64 v148, v153, v151, s[12:13]
	v_cmp_lt_f32_e64 s[12:13], 0, v159
	v_rcp_f32_e32 v151, v162
	v_cndmask_b32_e64 v147, v147, v150, s[10:11]
	v_cndmask_b32_e64 v149, v149, v156, s[14:15]
	v_cndmask_b32_e64 v148, v148, v152, s[12:13]
	v_mul_f32_e32 v150, 0x37800000, v147
	v_mul_f32_e32 v153, 0x37800000, v149
	v_mul_f32_e32 v152, 0x37800000, v148
	v_cndmask_b32_e64 v147, v147, v150, s[0:1]
	v_cndmask_b32_e64 v149, v149, v153, s[6:7]
	v_cmp_class_f32_e64 s[6:7], v143, v142
	v_cndmask_b32_e64 v148, v148, v152, s[4:5]
	v_cmp_class_f32_e64 s[0:1], v144, v142
	v_cmp_class_f32_e64 s[4:5], v145, v142
	v_cndmask_b32_e64 v143, v147, v143, s[6:7]
	v_cndmask_b32_e64 v147, v148, v144, s[0:1]
	v_cndmask_b32_e64 v145, v149, v145, s[4:5]
	v_fma_f32 v144, -v162, v151, 1.0
	v_div_scale_f32 v148, s[0:1], v143, v143, 1.0
	v_div_scale_f32 v163, vcc, 1.0, v146, 1.0
	v_div_scale_f32 v153, s[0:1], v145, v145, 1.0
	v_fmac_f32_e32 v151, v144, v151
	v_rcp_f32_e32 v155, v148
	v_div_scale_f32 v150, s[0:1], v147, v147, 1.0
	v_rcp_f32_e32 v157, v153
	v_mul_f32_e32 v144, v163, v151
	v_rcp_f32_e32 v156, v150
	v_fma_f32 v158, -v162, v144, v163
	v_fmac_f32_e32 v144, v158, v151
	v_fma_f32 v158, -v162, v144, v163
	v_fma_f32 v159, -v148, v155, 1.0
	v_div_scale_f32 v149, s[4:5], 1.0, v143, 1.0
	v_fma_f32 v161, -v153, v157, 1.0
	v_div_fmas_f32 v144, v158, v151, v144
	v_fmac_f32_e32 v155, v159, v155
	v_div_scale_f32 v154, s[0:1], 1.0, v145, 1.0
	v_fma_f32 v160, -v150, v156, 1.0
	v_fmac_f32_e32 v157, v161, v157
	v_div_fixup_f32 v144, v144, v146, 1.0
	v_mul_f32_e32 v146, v149, v155
	v_div_scale_f32 v152, s[6:7], 1.0, v147, 1.0
	v_fmac_f32_e32 v156, v160, v156
; __device__ __forceinline__ unsigned pk2(float lo, float hi) { return f2bf(lo) | (f2bf(hi) << 16); }
; template <int MODE, bool XB> __device__ __forceinline__ void norm_pass(const void* __restrict__ X, const float* __restrict__ g, const float* __restrict__ shift, const float* __restrict__ scale, ...
;     ...
; #pragma unroll
;             for (int j = 0; j < 4; ++j) {
;                 if (MODE == 0) { const f32x4 o = v[j] * rstd * gm[j] + sh[j]; v2u w; w.x = pk2(o[0], o[1]); w.y = pk2(o[2], o[3]); *(v2u*)(Hb + (size_t)(m0 + r) * D + 4 * lane + 256 * j) = w; }
;                 else { __builtin_nontemporal_store(v[j] * rstd * gm[j], (f32x4*)(Of + (size_t)(m0 + r) * D + 4 * lane + 256 * j)); }
;             }
	v_mul_f32_e32 v158, v154, v157
	v_pk_mul_f32 v[32:33], v[32:33], v[144:145] op_sel_hi:[1,0]
	v_pk_mul_f32 v[34:35], v[34:35], v[144:145] op_sel_hi:[1,0]
	v_pk_mul_f32 v[36:37], v[36:37], v[144:145] op_sel_hi:[1,0]
	v_pk_mul_f32 v[38:39], v[38:39], v[144:145] op_sel_hi:[1,0]
	v_pk_mul_f32 v[40:41], v[40:41], v[144:145] op_sel_hi:[1,0]
	v_pk_mul_f32 v[42:43], v[42:43], v[144:145] op_sel_hi:[1,0]
	v_pk_mul_f32 v[44:45], v[44:45], v[144:145] op_sel_hi:[1,0]
	v_pk_mul_f32 v[46:47], v[46:47], v[144:145] op_sel_hi:[1,0]
	v_fma_f32 v144, -v148, v146, v149
	v_mul_f32_e32 v151, v152, v156
	v_fma_f32 v160, -v153, v158, v154
	v_pk_fma_f32 v[34:35], v[110:111], v[34:35], v[18:19]
	v_pk_fma_f32 v[32:33], v[112:113], v[32:33], v[16:17]
	v_pk_fma_f32 v[38:39], v[114:115], v[38:39], v[22:23]
	v_pk_fma_f32 v[36:37], v[116:117], v[36:37], v[20:21]
	v_pk_fma_f32 v[42:43], v[118:119], v[42:43], v[26:27]
	v_fmac_f32_e32 v146, v144, v155
	v_fma_f32 v159, -v150, v151, v152
	v_pk_fma_f32 v[40:41], v[120:121], v[40:41], v[24:25]
	v_pk_fma_f32 v[46:47], v[122:123], v[46:47], v[30:31]
	v_pk_fma_f32 v[44:45], v[124:125], v[44:45], v[28:29]
	v_fmac_f32_e32 v158, v160, v157
	v_bfe_u32 v144, v32, 16, 1
	v_bfe_u32 v160, v34, 16, 1
	v_bfe_u32 v162, v36, 16, 1
	v_bfe_u32 v164, v38, 16, 1
	v_bfe_u32 v168, v42, 16, 1
	v_fma_f32 v148, -v148, v146, v149
	s_mov_b64 vcc, s[4:5]
	v_fmac_f32_e32 v151, v159, v156
	v_bfe_u32 v159, v33, 16, 1
	v_bfe_u32 v161, v35, 16, 1
	v_bfe_u32 v163, v37, 16, 1
	v_bfe_u32 v165, v39, 16, 1
	v_bfe_u32 v166, v40, 16, 1
	v_bfe_u32 v169, v43, 16, 1
	v_bfe_u32 v170, v44, 16, 1
	v_bfe_u32 v172, v46, 16, 1
	v_add3_u32 v32, v32, v144, s36
	v_add3_u32 v34, v34, v160, s36
	v_add3_u32 v36, v36, v162, s36
	v_add3_u32 v38, v38, v164, s36
	v_add3_u32 v42, v42, v168, s36
	v_div_fmas_f32 v144, v148, v155, v146
	v_bfe_u32 v167, v41, 16, 1
	v_bfe_u32 v171, v45, 16, 1
	v_bfe_u32 v173, v47, 16, 1
	v_fma_f32 v149, -v150, v151, v152
	v_add3_u32 v33, v33, v159, s36
	v_add3_u32 v35, v35, v161, s36
	v_add3_u32 v37, v37, v163, s36
	v_add3_u32 v39, v39, v165, s36
	v_add3_u32 v40, v40, v166, s36
	v_add3_u32 v43, v43, v169, s36
	v_add3_u32 v44, v44, v170, s36
	v_add3_u32 v46, v46, v172, s36
	v_lshrrev_b32_e32 v146, 16, v32
	v_lshrrev_b32_e32 v148, 16, v34
	v_lshrrev_b32_e32 v36, 16, v36
	v_lshrrev_b32_e32 v38, 16, v38
	v_lshrrev_b32_e32 v42, 16, v42
	v_div_fixup_f32 v32, v144, v143, 1.0
	s_mov_b64 vcc, s[6:7]
	v_fma_f32 v150, -v153, v158, v154
	v_add3_u32 v41, v41, v167, s36
	v_add3_u32 v45, v45, v171, s36
	v_add3_u32 v47, v47, v173, s36
	v_lshrrev_b32_e32 v40, 16, v40
	v_lshrrev_b32_e32 v44, 16, v44
	v_lshrrev_b32_e32 v46, 16, v46
	v_div_fmas_f32 v143, v149, v156, v151
	v_and_or_b32 v34, v33, s37, v146
	v_and_or_b32 v35, v35, s37, v148
	v_and_or_b32 v36, v37, s37, v36
	v_and_or_b32 v37, v39, s37, v38
	v_and_or_b32 v39, v43, s37, v42
	v_pk_mul_f32 v[42:43], v[92:93], v[32:33] op_sel_hi:[1,0]
	s_mov_b64 vcc, s[0:1]
	v_and_or_b32 v38, v41, s37, v40
	v_and_or_b32 v40, v45, s37, v44
	v_and_or_b32 v41, v47, s37, v46
	v_pk_mul_f32 v[44:45], v[94:95], v[32:33] op_sel_hi:[1,0]
	v_pk_mul_f32 v[46:47], v[84:85], v[32:33] op_sel_hi:[1,0]
	v_pk_mul_f32 v[84:85], v[86:87], v[32:33] op_sel_hi:[1,0]
	v_pk_mul_f32 v[86:87], v[88:89], v[32:33] op_sel_hi:[1,0]
	v_pk_mul_f32 v[88:89], v[90:91], v[32:33] op_sel_hi:[1,0]
	v_pk_mul_f32 v[80:81], v[80:81], v[32:33] op_sel_hi:[1,0]
	v_pk_mul_f32 v[32:33], v[82:83], v[32:33] op_sel_hi:[1,0]
	v_div_fixup_f32 v82, v143, v147, 1.0
	v_div_fmas_f32 v83, v150, v157, v158
	global_store_dwordx2 v[108:109], v[34:35], off offset:-1024
	global_store_dwordx2 v[108:109], v[36:37], off offset:-512
	global_store_dwordx2 v[108:109], v[38:39], off
	global_store_dwordx2 v[108:109], v[40:41], off offset:512
	v_pk_fma_f32 v[36:37], v[112:113], v[42:43], v[16:17]
	v_pk_fma_f32 v[34:35], v[110:111], v[44:45], v[18:19]
	v_pk_fma_f32 v[38:39], v[114:115], v[84:85], v[22:23]
	v_pk_fma_f32 v[40:41], v[116:117], v[46:47], v[20:21]
	v_pk_fma_f32 v[42:43], v[118:119], v[88:89], v[26:27]
	v_pk_fma_f32 v[44:45], v[120:121], v[86:87], v[24:25]
	v_pk_fma_f32 v[32:33], v[122:123], v[32:33], v[30:31]
	v_pk_fma_f32 v[46:47], v[124:125], v[80:81], v[28:29]
	v_pk_mul_f32 v[76:77], v[76:77], v[82:83] op_sel_hi:[1,0]
	v_pk_mul_f32 v[78:79], v[78:79], v[82:83] op_sel_hi:[1,0]
	v_pk_mul_f32 v[68:69], v[68:69], v[82:83] op_sel_hi:[1,0]
	v_pk_mul_f32 v[70:71], v[70:71], v[82:83] op_sel_hi:[1,0]
	v_pk_mul_f32 v[72:73], v[72:73], v[82:83] op_sel_hi:[1,0]
	v_pk_mul_f32 v[74:75], v[74:75], v[82:83] op_sel_hi:[1,0]
	v_div_fixup_f32 v80, v83, v145, 1.0
	v_bfe_u32 v81, v36, 16, 1
	v_pk_mul_f32 v[64:65], v[64:65], v[82:83] op_sel_hi:[1,0]
	v_pk_mul_f32 v[66:67], v[66:67], v[82:83] op_sel_hi:[1,0]
	v_bfe_u32 v82, v37, 16, 1
	v_bfe_u32 v83, v34, 16, 1
	v_bfe_u32 v84, v35, 16, 1
	v_bfe_u32 v85, v40, 16, 1
	v_bfe_u32 v86, v41, 16, 1
	v_bfe_u32 v87, v38, 16, 1
	v_bfe_u32 v88, v39, 16, 1
	v_bfe_u32 v89, v44, 16, 1
	v_bfe_u32 v90, v45, 16, 1
	v_bfe_u32 v91, v42, 16, 1
	v_bfe_u32 v92, v43, 16, 1
	v_bfe_u32 v93, v46, 16, 1
	v_bfe_u32 v94, v47, 16, 1
	v_bfe_u32 v95, v32, 16, 1
	v_bfe_u32 v143, v33, 16, 1
	v_pk_fma_f32 v[78:79], v[110:111], v[78:79], v[18:19]
	v_pk_fma_f32 v[76:77], v[112:113], v[76:77], v[16:17]
	v_pk_fma_f32 v[70:71], v[114:115], v[70:71], v[22:23]
	v_pk_fma_f32 v[68:69], v[116:117], v[68:69], v[20:21]
	v_pk_fma_f32 v[74:75], v[118:119], v[74:75], v[26:27]
	v_pk_fma_f32 v[72:73], v[120:121], v[72:73], v[24:25]
	v_pk_mul_f32 v[60:61], v[60:61], v[80:81] op_sel_hi:[1,0]
	v_pk_mul_f32 v[62:63], v[62:63], v[80:81] op_sel_hi:[1,0]
	v_pk_fma_f32 v[66:67], v[122:123], v[66:67], v[30:31]
; __device__ __forceinline__ unsigned pk2(float lo, float hi) { return f2bf(lo) | (f2bf(hi) << 16); }
; template <int MODE, bool XB> __device__ __forceinline__ void norm_pass(const void* __restrict__ X, const float* __restrict__ g, const float* __restrict__ shift, const float* __restrict__ scale, ...
;     ...
;     for (int m0 = gw * 16; m0 < M; m0 += NGW * 16) {
;         const int b = m0 / SEQ;
;         f32x4 gm[4], sh[4];
; #pragma unroll
;         for (int j = 0; j < 4; ++j) { const int col = 4 * lane + 256 * j; gm[j] = *(const f32x4*)(g + col);
;             if (MODE == 0) { gm[j] = gm[j] * (*(const f32x4*)(scale + (size_t)b * NMOD9 + col) + 1.0f); sh[j] = *(const f32x4*)(shift + (size_t)b * NMOD9 + col); } }
; #pragma unroll 4
;         for (int r = 0; r < 16; ++r) {
;             f32x4 v[4]; float s = 0.f;
; #pragma unroll
;             for (int j = 0; j < 4; ++j) {
;                 if constexpr (XB) { const v2u w = *(const v2u*)((const bf16*)X + (size_t)(m0 + r) * D + 4 * lane + 256 * j);
;                     v[j] = (f32x4){__uint_as_float(w.x << 16), __uint_as_float(w.x & 0xffff0000u), __uint_as_float(w.y << 16), __uint_as_float(w.y & 0xffff0000u)}; }
;                 else v[j] = *(const f32x4*)((const float*)X + (size_t)(m0 + r) * D + 4 * lane + 256 * j);
;                 s += (v[j][0] * v[j][0] + v[j][1] * v[j][1]) + (v[j][2] * v[j][2] + v[j][3] * v[j][3]); }
;             const float rstd = 1.0f / sqrtf(wave_sum(s) * (1.f / D) + 1e-6f);
; #pragma unroll
;             for (int j = 0; j < 4; ++j) {
;                 if (MODE == 0) { const f32x4 o = v[j] * rstd * gm[j] + sh[j]; v2u w; w.x = pk2(o[0], o[1]); w.y = pk2(o[2], o[3]); *(v2u*)(Hb + (size_t)(m0 + r) * D + 4 * lane + 256 * j) = w; }
;                 else { __builtin_nontemporal_store(v[j] * rstd * gm[j], (f32x4*)(Of + (size_t)(m0 + r) * D + 4 * lane + 256 * j)); }
;             }
;         }
	v_pk_fma_f32 v[64:65], v[124:125], v[64:65], v[28:29]
	v_pk_mul_f32 v[52:53], v[52:53], v[80:81] op_sel_hi:[1,0]
	v_pk_mul_f32 v[54:55], v[54:55], v[80:81] op_sel_hi:[1,0]
	v_pk_mul_f32 v[56:57], v[56:57], v[80:81] op_sel_hi:[1,0]
	v_pk_mul_f32 v[58:59], v[58:59], v[80:81] op_sel_hi:[1,0]
	v_pk_mul_f32 v[48:49], v[48:49], v[80:81] op_sel_hi:[1,0]
	v_pk_mul_f32 v[50:51], v[50:51], v[80:81] op_sel_hi:[1,0]
	v_add3_u32 v80, v36, v81, s36
	v_add3_u32 v81, v37, v82, s36
	v_add3_u32 v82, v34, v83, s36
	v_add3_u32 v83, v35, v84, s36
	v_add3_u32 v84, v40, v85, s36
	v_add3_u32 v85, v41, v86, s36
	v_add3_u32 v86, v38, v87, s36
	v_add3_u32 v87, v39, v88, s36
	v_add3_u32 v88, v44, v89, s36
	v_add3_u32 v89, v45, v90, s36
	v_add3_u32 v90, v42, v91, s36
	v_add3_u32 v91, v43, v92, s36
	v_add3_u32 v92, v46, v93, s36
	v_add3_u32 v93, v47, v94, s36
	v_add3_u32 v94, v32, v95, s36
	v_add3_u32 v95, v33, v143, s36
	v_bfe_u32 v143, v76, 16, 1
	v_bfe_u32 v145, v78, 16, 1
	v_bfe_u32 v147, v68, 16, 1
	v_bfe_u32 v149, v70, 16, 1
	v_bfe_u32 v151, v72, 16, 1
	v_bfe_u32 v153, v74, 16, 1
	v_pk_fma_f32 v[32:33], v[110:111], v[62:63], v[18:19]
	v_pk_fma_f32 v[34:35], v[112:113], v[60:61], v[16:17]
	v_bfe_u32 v144, v77, 16, 1
	v_bfe_u32 v146, v79, 16, 1
	v_bfe_u32 v148, v69, 16, 1
	v_bfe_u32 v150, v71, 16, 1
	v_bfe_u32 v152, v73, 16, 1
	v_bfe_u32 v154, v75, 16, 1
	v_bfe_u32 v155, v64, 16, 1
	v_bfe_u32 v157, v66, 16, 1
	v_pk_fma_f32 v[36:37], v[114:115], v[54:55], v[22:23]
	v_pk_fma_f32 v[38:39], v[116:117], v[52:53], v[20:21]
	v_pk_fma_f32 v[40:41], v[118:119], v[58:59], v[26:27]
	v_pk_fma_f32 v[42:43], v[120:121], v[56:57], v[24:25]
	v_pk_fma_f32 v[44:45], v[122:123], v[50:51], v[30:31]
	v_pk_fma_f32 v[46:47], v[124:125], v[48:49], v[28:29]
	v_lshrrev_b32_e32 v48, 16, v80
	v_lshrrev_b32_e32 v49, 16, v82
	v_add3_u32 v56, v76, v143, s36
	v_add3_u32 v58, v78, v145, s36
	v_add3_u32 v60, v68, v147, s36
	v_add3_u32 v62, v70, v149, s36
	v_add3_u32 v68, v72, v151, s36
	v_add3_u32 v70, v74, v153, s36
	v_bfe_u32 v72, v34, 16, 1
	v_bfe_u32 v74, v32, 16, 1
	v_bfe_u32 v156, v65, 16, 1
	v_bfe_u32 v158, v67, 16, 1
	v_lshrrev_b32_e32 v50, 16, v84
	v_lshrrev_b32_e32 v51, 16, v86
	v_lshrrev_b32_e32 v52, 16, v88
	v_lshrrev_b32_e32 v53, 16, v90
	v_lshrrev_b32_e32 v54, 16, v92
	v_lshrrev_b32_e32 v55, 16, v94
	v_add3_u32 v57, v77, v144, s36
	v_add3_u32 v59, v79, v146, s36
	v_add3_u32 v61, v69, v148, s36
	v_add3_u32 v63, v71, v150, s36
	v_add3_u32 v69, v73, v152, s36
	v_add3_u32 v71, v75, v154, s36
	v_add3_u32 v64, v64, v155, s36
	v_add3_u32 v66, v66, v157, s36
	v_bfe_u32 v73, v35, 16, 1
	v_bfe_u32 v75, v33, 16, 1
	v_bfe_u32 v76, v38, 16, 1
	v_bfe_u32 v78, v36, 16, 1
	v_bfe_u32 v80, v42, 16, 1
	v_bfe_u32 v84, v40, 16, 1
	v_bfe_u32 v88, v46, 16, 1
	v_bfe_u32 v92, v44, 16, 1
	v_and_or_b32 v48, v81, s37, v48
	v_and_or_b32 v49, v83, s37, v49
	v_lshrrev_b32_e32 v56, 16, v56
	v_lshrrev_b32_e32 v58, 16, v58
	v_add3_u32 v72, v34, v72, s36
	v_add3_u32 v74, v32, v74, s36
	v_add3_u32 v65, v65, v156, s36
	v_add3_u32 v67, v67, v158, s36
	v_bfe_u32 v77, v39, 16, 1
	v_bfe_u32 v79, v37, 16, 1
	v_bfe_u32 v82, v43, 16, 1
	v_bfe_u32 v86, v41, 16, 1
	v_bfe_u32 v90, v47, 16, 1
	v_bfe_u32 v94, v45, 16, 1
	v_and_or_b32 v50, v85, s37, v50
	v_and_or_b32 v51, v87, s37, v51
	v_and_or_b32 v52, v89, s37, v52
	v_and_or_b32 v53, v91, s37, v53
	v_and_or_b32 v54, v93, s37, v54
	v_and_or_b32 v55, v95, s37, v55
	v_lshrrev_b32_e32 v60, 16, v60
	v_lshrrev_b32_e32 v62, 16, v62
	v_lshrrev_b32_e32 v68, 16, v68
	v_lshrrev_b32_e32 v70, 16, v70
	v_lshrrev_b32_e32 v64, 16, v64
	v_lshrrev_b32_e32 v66, 16, v66
	v_add3_u32 v73, v35, v73, s36
	v_add3_u32 v75, v33, v75, s36
	v_add3_u32 v76, v38, v76, s36
	v_add3_u32 v78, v36, v78, s36
	v_add3_u32 v42, v42, v80, s36
	v_add3_u32 v40, v40, v84, s36
	v_add3_u32 v46, v46, v88, s36
	v_add3_u32 v44, v44, v92, s36
	global_store_dwordx2 v[132:133], v[48:49], off
	global_store_dwordx2 v[132:133], v[50:51], off offset:512
	global_store_dwordx2 v[132:133], v[52:53], off offset:1024
	global_store_dwordx2 v[132:133], v[54:55], off offset:1536
	v_and_or_b32 v32, v57, s37, v56
	v_and_or_b32 v33, v59, s37, v58
	v_lshrrev_b32_e32 v48, 16, v72
	v_lshrrev_b32_e32 v49, 16, v74
	v_lshl_add_u64 v[108:109], v[108:109], 0, s[78:79]
	v_add3_u32 v77, v39, v77, s36
	v_add3_u32 v79, v37, v79, s36
	v_add3_u32 v43, v43, v82, s36
	v_add3_u32 v41, v41, v86, s36
	v_add3_u32 v47, v47, v90, s36
	v_add3_u32 v45, v45, v94, s36
	v_and_or_b32 v34, v61, s37, v60
	v_and_or_b32 v35, v63, s37, v62
	v_and_or_b32 v36, v69, s37, v68
	v_and_or_b32 v37, v71, s37, v70
	v_and_or_b32 v38, v65, s37, v64
	v_and_or_b32 v39, v67, s37, v66
	v_lshrrev_b32_e32 v50, 16, v76
	v_lshrrev_b32_e32 v51, 16, v78
	v_lshrrev_b32_e32 v42, 16, v42
	v_lshrrev_b32_e32 v40, 16, v40
	v_lshrrev_b32_e32 v46, 16, v46
	v_lshrrev_b32_e32 v44, 16, v44
	global_store_dwordx2 v[130:131], v[32:33], off
	global_store_dwordx2 v[130:131], v[34:35], off offset:512
	global_store_dwordx2 v[130:131], v[36:37], off offset:1024
	global_store_dwordx2 v[130:131], v[38:39], off offset:1536
	v_and_or_b32 v32, v73, s37, v48
	v_and_or_b32 v33, v75, s37, v49
	v_and_or_b32 v34, v77, s37, v50
	v_and_or_b32 v35, v79, s37, v51
	v_and_or_b32 v36, v43, s37, v42
	v_and_or_b32 v37, v41, s37, v40
	v_and_or_b32 v38, v47, s37, v46
	v_and_or_b32 v39, v45, s37, v44
	global_store_dwordx2 v[128:129], v[32:33], off
	global_store_dwordx2 v[128:129], v[34:35], off offset:512
	global_store_dwordx2 v[128:129], v[36:37], off offset:1024
	global_store_dwordx2 v[128:129], v[38:39], off offset:1536
	s_cbranch_scc1 .LBB0_51
	s_add_i32 s54, s54, s58
	v_lshl_add_u64 v[104:105], v[104:105], 0, s[60:61]
	s_cmp_lt_i32 s54, 0x8000
	v_lshl_add_u64 v[106:107], v[106:107], 0, s[72:73]
	s_cbranch_scc1 .LBB0_50

; #define LAS __attribute__((address_space(3)))
; template <class RM> __device__ __forceinline__ void tr_item(const float* __restrict__ W, int K, int N, bf16* __restrict__ WT, RM rm, const float* ks0, const float* ks1, int ksplit, LAS float* scr, int item, int lane) {
;     const int nblk = N / 32, kb = item / nblk, nb = item % nblk, k0 = 64 * kb, n0 = 32 * nb;
;     f32x4 wv[8];
;     const int r8 = lane >> 3, cg = lane & 7;
; #pragma unroll
;     for (int i = 0; i < 8; ++i) wv[i] = *(const f32x4*)(W + (size_t)(k0 + 8 * i + r8) * N + n0 + 4 * cg);
;     const f32x4 cs = {rm.scale(n0 + 4 * cg), rm.scale(n0 + 4 * cg + 1), rm.scale(n0 + 4 * cg + 2), rm.scale(n0 + 4 * cg + 3)};
; #pragma unroll
;     for (int i = 0; i < 8; ++i) { const int kk = 8 * i + r8; f32x4 w = wv[i] * cs;
;         if (ks0) { const int k = k0 + kk; w = w * ((k < ksplit) ? ks0[k] : ks1[k - ksplit]); }
; __global__ void __launch_bounds__(512) fwd_megakernel(Args a) {
;     ...
;         for (int it = gw; it < NITEMS; it += NGW) {
;             int r = it;
;             if (r < I_GU) { tr_item(a.in[5], D, 2 * DFF, WGU1, RmGu{}, nullptr, nullptr, 0, scr, r, lane); continue; } r -= I_GU;
;             if (r < I_DN) { tr_item(a.in[6], DFF, D, WD1, RmId{}, nullptr, nullptr, 0, scr, r, lane); continue; } r -= I_DN;
;             if (r < I_GU) { tr_item(a.in[19], D, 2 * DFF, WGU2, RmGu{}, nullptr, nullptr, 0, scr, r, lane); continue; } r -= I_GU;
;             if (r < I_DN) { tr_item(a.in[20], DFF, D, WD2, RmId{}, nullptr, nullptr, 0, scr, r, lane); continue; } r -= I_DN;
;             if (r < I_IN) { tr_item(a.in[8], D, DIN, WIN, RmWin{}, nullptr, nullptr, 0, scr, r, lane); continue; } r -= I_IN;
;             if (r < I_UQ) { tr_item(a.in[10], 256, 768, WUQ, RmUq{}, a.in[9], a.in[9], 256, scr, r, lane); continue; } r -= I_UQ;
;             if (r < I_UKV) { tr_item(a.in[12], 128, 1024, WUKV, RmUkv{}, a.in[11], a.in[11], 128, scr, r, lane); continue; } r -= I_UKV;
;             tr_item(a.in[17], D, D, WOUT, RmId{}, a.in[15], a.in[16], 512, scr, r, lane);
.LBB0_56:
	s_cmpk_gt_i32 s3, 0xaff
	s_mov_b64 s[0:1], -1
	s_cbranch_scc0 .LBB0_199
	s_cmpk_gt_u32 s3, 0x107f
	s_cbranch_scc0 .LBB0_196
	s_cmpk_gt_u32 s3, 0x1b7f
	s_cbranch_scc0 .LBB0_193
	s_cmpk_gt_u32 s3, 0x20ff
	s_cbranch_scc0 .LBB0_190
	s_cmpk_gt_u32 s3, 0x234f
	s_cbranch_scc0 .LBB0_121
	s_cmpk_gt_u32 s3, 0x23af
	s_cbranch_scc0 .LBB0_90
	s_cmpk_gt_u32 s3, 0x23ef
	s_cbranch_scc0 .LBB0_76
	s_add_i32 s0, s9, 0xfffb8200
	s_and_b32 s18, s39, 0xfc0
	s_and_b32 s33, s0, 0x3e0
	v_or_b32_e32 v32, s18, v76
	s_lshl_b32 s0, s33, 2
	s_mov_b32 s1, s19
	v_lshl_add_u64 v[0:1], v[38:39], 0, s[0:1]
	v_lshlrev_b32_e32 v36, 12, v32
	v_lshl_add_u64 v[0:1], v[0:1], 0, v[36:37]
	v_add_co_u32_e32 v2, vcc, 0x8000, v0
	v_cmp_ne_u32_e64 s[0:1], 1, v95
	s_nop 0
	v_addc_co_u32_e32 v3, vcc, 0, v1, vcc
	global_load_dwordx4 v[24:27], v[0:1], off nt
	global_load_dwordx4 v[28:31], v[2:3], off nt
	v_add_co_u32_e32 v2, vcc, 0x10000, v0
	v_add_lshl_u32 v70, s18, v76, 2
	s_nop 0
	v_addc_co_u32_e32 v3, vcc, 0, v1, vcc
	v_add_co_u32_e32 v4, vcc, 0x18000, v0
	s_nop 1
	v_addc_co_u32_e32 v5, vcc, 0, v1, vcc
	global_load_dwordx4 v[16:19], v[2:3], off nt
	global_load_dwordx4 v[20:23], v[4:5], off nt
	v_add_co_u32_e32 v2, vcc, 0x20000, v0
	s_nop 1
	v_addc_co_u32_e32 v3, vcc, 0, v1, vcc
	v_add_co_u32_e32 v4, vcc, 0x28000, v0
	s_nop 1
	v_addc_co_u32_e32 v5, vcc, 0, v1, vcc
	global_load_dwordx4 v[8:11], v[2:3], off nt
	global_load_dwordx4 v[12:15], v[4:5], off nt
	v_add_co_u32_e32 v2, vcc, 0x30000, v0
	s_nop 1
	v_addc_co_u32_e32 v3, vcc, 0, v1, vcc
	v_add_co_u32_e32 v4, vcc, 0x38000, v0
	s_nop 1
	v_addc_co_u32_e32 v5, vcc, 0, v1, vcc
	global_load_dwordx4 v[0:3], v[2:3], off nt
	s_nop 0
	global_load_dwordx4 v[4:7], v[4:5], off nt
	s_andn2_b64 vcc, exec, s[10:11]
	s_cbranch_vccnz .LBB0_206
	v_lshlrev_b32_e32 v36, 2, v32
	v_readlane_b32 s80, v255, 7
	s_movk_i32 s58, 0xf800
	s_cmpk_lt_u32 s18, 0x200
	v_readlane_b32 s94, v255, 21
	v_readlane_b32 s95, v255, 22
	v_lshl_add_u64 v[34:35], s[16:17], 0, v[36:37]
	s_mov_b32 s59, -1
	v_lshl_add_u64 v[32:33], s[94:95], 0, v[36:37]
	v_lshl_add_u64 v[34:35], v[34:35], 0, s[58:59]
	s_cselect_b64 vcc, -1, 0
	v_mov_b32_e32 v71, v37
	s_movk_i32 s58, 0xf820
	v_cndmask_b32_e32 v33, v35, v33, vcc
	v_cndmask_b32_e32 v32, v34, v32, vcc
	v_lshl_add_u64 v[34:35], s[94:95], 0, v[70:71]
	v_lshl_add_u64 v[72:73], s[16:17], 0, v[70:71]
	s_mov_b32 s59, -1
	v_lshl_add_u64 v[34:35], v[34:35], 0, 32
	v_lshl_add_u64 v[72:73], v[72:73], 0, s[58:59]
	v_cndmask_b32_e32 v35, v73, v35, vcc
	v_cndmask_b32_e32 v34, v72, v34, vcc
	global_load_dword v32, v[32:33], off
	s_nop 0
	global_load_dword v36, v[34:35], off
	v_readlane_b32 s81, v255, 8
	v_readlane_b32 s82, v255, 9
	v_readlane_b32 s83, v255, 10
	v_readlane_b32 s84, v255, 11
	v_readlane_b32 s85, v255, 12
	v_readlane_b32 s86, v255, 13
	v_readlane_b32 s87, v255, 14
	v_readlane_b32 s88, v255, 15
	v_readlane_b32 s89, v255, 16
	v_readlane_b32 s90, v255, 17
	v_readlane_b32 s91, v255, 18
	v_readlane_b32 s92, v255, 19
	v_readlane_b32 s93, v255, 20
	s_waitcnt vmcnt(1)
	v_pk_mul_f32 v[72:73], v[26:27], v[32:33] op_sel_hi:[1,0]
	v_pk_mul_f32 v[74:75], v[24:25], v[32:33] op_sel_hi:[1,0]
	s_waitcnt vmcnt(0)
	v_pk_mul_f32 v[34:35], v[30:31], v[36:37] op_sel_hi:[1,0]
	v_pk_mul_f32 v[32:33], v[28:29], v[36:37] op_sel_hi:[1,0]
	s_cbranch_execnz .LBB0_66

; #define LAS __attribute__((address_space(3)))
; template <class RM> __device__ __forceinline__ void tr_item(const float* __restrict__ W, int K, int N, bf16* __restrict__ WT, RM rm, const float* ks0, const float* ks1, int ksplit, LAS float* scr, int item, int lane) {
;     const int nblk = N / 32, kb = item / nblk, nb = item % nblk, k0 = 64 * kb, n0 = 32 * nb;
;     f32x4 wv[8];
;     const int r8 = lane >> 3, cg = lane & 7;
; #pragma unroll
;     for (int i = 0; i < 8; ++i) wv[i] = *(const f32x4*)(W + (size_t)(k0 + 8 * i + r8) * N + n0 + 4 * cg);
;     const f32x4 cs = {rm.scale(n0 + 4 * cg), rm.scale(n0 + 4 * cg + 1), rm.scale(n0 + 4 * cg + 2), rm.scale(n0 + 4 * cg + 3)};
; #pragma unroll
;     for (int i = 0; i < 8; ++i) { const int kk = 8 * i + r8; f32x4 w = wv[i] * cs;
;         if (ks0) { const int k = k0 + kk; w = w * ((k < ksplit) ? ks0[k] : ks1[k - ksplit]); }
; __global__ void __launch_bounds__(512) fwd_megakernel(Args a) {
;     ...
;             if (r < I_UKV) { tr_item(a.in[12], 128, 1024, WUKV, RmUkv{}, a.in[11], a.in[11], 128, scr, r, lane); continue; } r -= I_UKV;
.LBB0_76:
	s_and_b64 vcc, exec, s[0:1]
	s_cbranch_vccz .LBB0_201
	s_add_i32 s0, s39, 0x80
	s_add_i32 s58, s9, 0xfffb8a00
	s_and_b32 s33, s0, 64
	s_and_b32 s0, s58, 0x3e0
	v_or_b32_e32 v32, s33, v76
	s_lshl_b32 s18, s0, 2
	v_lshl_add_u64 v[0:1], v[42:43], 0, s[18:19]
	v_lshlrev_b32_e32 v36, 12, v32
	v_lshl_add_u64 v[0:1], v[0:1], 0, v[36:37]
	v_add_co_u32_e32 v2, vcc, 0x8000, v0
	v_cndmask_b32_e64 v33, 0, 1, s[12:13]
	s_nop 0
	v_addc_co_u32_e32 v3, vcc, 0, v1, vcc
	global_load_dwordx4 v[24:27], v[0:1], off nt
	global_load_dwordx4 v[28:31], v[2:3], off nt
	v_add_co_u32_e32 v2, vcc, 0x10000, v0
	v_cmp_ne_u32_e64 s[0:1], 1, v33
	s_nop 0
	v_addc_co_u32_e32 v3, vcc, 0, v1, vcc
	v_add_co_u32_e32 v4, vcc, 0x18000, v0
	v_add_lshl_u32 v36, s33, v76, 2
	s_nop 0
	v_addc_co_u32_e32 v5, vcc, 0, v1, vcc
	global_load_dwordx4 v[16:19], v[2:3], off nt
	global_load_dwordx4 v[20:23], v[4:5], off nt
	v_add_co_u32_e32 v2, vcc, 0x20000, v0
	s_nop 1
	v_addc_co_u32_e32 v3, vcc, 0, v1, vcc
	v_add_co_u32_e32 v4, vcc, 0x28000, v0
	s_nop 1
	v_addc_co_u32_e32 v5, vcc, 0, v1, vcc
	global_load_dwordx4 v[8:11], v[2:3], off nt
	global_load_dwordx4 v[12:15], v[4:5], off nt
	v_add_co_u32_e32 v2, vcc, 0x30000, v0
	s_nop 1
	v_addc_co_u32_e32 v3, vcc, 0, v1, vcc
	v_add_co_u32_e32 v4, vcc, 0x38000, v0
	s_nop 1
	v_addc_co_u32_e32 v5, vcc, 0, v1, vcc
	global_load_dwordx4 v[0:3], v[2:3], off nt
	s_nop 0
	global_load_dwordx4 v[4:7], v[4:5], off nt
	s_andn2_b64 vcc, exec, s[12:13]
	s_cbranch_vccnz .LBB0_210
	v_readlane_b32 s80, v255, 7
	v_lshlrev_b32_e32 v32, 2, v32
	v_readlane_b32 s86, v255, 13
	v_readlane_b32 s87, v255, 14
	s_nop 4
	global_load_dword v32, v32, s[86:87]
	s_nop 0
	global_load_dword v74, v36, s[86:87] offset:32
	v_readlane_b32 s81, v255, 8
	v_readlane_b32 s82, v255, 9
	v_readlane_b32 s83, v255, 10
	v_readlane_b32 s84, v255, 11
	v_readlane_b32 s85, v255, 12
	v_readlane_b32 s88, v255, 15
	v_readlane_b32 s89, v255, 16
	v_readlane_b32 s90, v255, 17
	v_readlane_b32 s91, v255, 18
	v_readlane_b32 s92, v255, 19
	v_readlane_b32 s93, v255, 20
	v_readlane_b32 s94, v255, 21
	v_readlane_b32 s95, v255, 22
	s_waitcnt vmcnt(1)
	v_pk_mul_f32 v[70:71], v[26:27], v[32:33] op_sel_hi:[1,0]
	v_pk_mul_f32 v[72:73], v[24:25], v[32:33] op_sel_hi:[1,0]
	s_waitcnt vmcnt(0)
	v_pk_mul_f32 v[34:35], v[30:31], v[74:75] op_sel_hi:[1,0]
	v_pk_mul_f32 v[32:33], v[28:29], v[74:75] op_sel_hi:[1,0]
	s_cbranch_execnz .LBB0_80

; #define LAS __attribute__((address_space(3)))
; template <class RM> __device__ __forceinline__ void tr_item(const float* __restrict__ W, int K, int N, bf16* __restrict__ WT, RM rm, const float* ks0, const float* ks1, int ksplit, LAS float* scr, int item, int lane) {
;     const int nblk = N / 32, kb = item / nblk, nb = item % nblk, k0 = 64 * kb, n0 = 32 * nb;
;     f32x4 wv[8];
;     const int r8 = lane >> 3, cg = lane & 7;
; #pragma unroll
;     for (int i = 0; i < 8; ++i) wv[i] = *(const f32x4*)(W + (size_t)(k0 + 8 * i + r8) * N + n0 + 4 * cg);
;     const f32x4 cs = {rm.scale(n0 + 4 * cg), rm.scale(n0 + 4 * cg + 1), rm.scale(n0 + 4 * cg + 2), rm.scale(n0 + 4 * cg + 3)};
; #pragma unroll
;     for (int i = 0; i < 8; ++i) { const int kk = 8 * i + r8; f32x4 w = wv[i] * cs;
;         if (ks0) { const int k = k0 + kk; w = w * ((k < ksplit) ? ks0[k] : ks1[k - ksplit]); }
; __global__ void __launch_bounds__(512) fwd_megakernel(Args a) {
;     ...
;             if (r < I_UQ) { tr_item(a.in[10], 256, 768, WUQ, RmUq{}, a.in[9], a.in[9], 256, scr, r, lane); continue; } r -= I_UQ;
.LBB0_91:
	s_add_i32 s0, s3, 0xffb0
	s_and_b32 s1, s0, 0xff
	s_mulk_i32 s1, 0xab
	s_bfe_u32 s1, s1, 0x4000c
	s_mul_i32 s18, s1, 24
	s_sub_i32 s0, s0, s18
	s_lshl_b32 s33, s1, 6
	s_and_b32 s58, s0, 0xff
	v_or_b32_e32 v32, s33, v76
	s_lshl_b32 s18, s58, 7
	v_mul_u32_u24_e32 v2, 0x300, v32
	v_lshl_add_u64 v[0:1], v[46:47], 0, s[18:19]
	v_lshlrev_b32_e32 v36, 2, v2
	v_lshl_add_u64 v[0:1], v[0:1], 0, v[36:37]
	s_movk_i32 s0, 0x6000
	v_add_co_u32_e32 v2, vcc, s0, v0
	s_mov_b32 s0, 0xc000
	s_nop 0
	v_addc_co_u32_e32 v3, vcc, 0, v1, vcc
	global_load_dwordx4 v[24:27], v[0:1], off nt
	global_load_dwordx4 v[28:31], v[2:3], off nt
	v_add_co_u32_e32 v2, vcc, s0, v0
	s_mov_b32 s0, 0x18000
	s_nop 0
	v_addc_co_u32_e32 v3, vcc, 0, v1, vcc
	v_add_co_u32_e32 v4, vcc, s51, v0
	v_cndmask_b32_e64 v33, 0, 1, s[14:15]
	s_nop 0
	v_addc_co_u32_e32 v5, vcc, 0, v1, vcc
	global_load_dwordx4 v[16:19], v[2:3], off nt
	global_load_dwordx4 v[20:23], v[4:5], off nt
	v_add_co_u32_e32 v2, vcc, s0, v0
	v_cmp_ne_u32_e64 s[0:1], 1, v33
	s_nop 0
	v_addc_co_u32_e32 v3, vcc, 0, v1, vcc
	v_add_co_u32_e32 v4, vcc, 0x1e000, v0
	v_add_lshl_u32 v36, s33, v76, 2
	s_nop 0
	v_addc_co_u32_e32 v5, vcc, 0, v1, vcc
	global_load_dwordx4 v[8:11], v[2:3], off nt
	global_load_dwordx4 v[12:15], v[4:5], off nt
	v_add_co_u32_e32 v2, vcc, 0x24000, v0
	s_nop 1
	v_addc_co_u32_e32 v3, vcc, 0, v1, vcc
	v_add_co_u32_e32 v4, vcc, 0x2a000, v0
	s_nop 1
	v_addc_co_u32_e32 v5, vcc, 0, v1, vcc
	global_load_dwordx4 v[0:3], v[2:3], off nt
	s_nop 0
	global_load_dwordx4 v[4:7], v[4:5], off nt
	s_andn2_b64 vcc, exec, s[14:15]
	s_cbranch_vccnz .LBB0_202
	v_readlane_b32 s80, v255, 7
	v_lshlrev_b32_e32 v32, 2, v32
	v_readlane_b32 s82, v255, 9
	v_readlane_b32 s83, v255, 10
	s_nop 4
	global_load_dword v32, v32, s[82:83]
	s_nop 0
	global_load_dword v74, v36, s[82:83] offset:32
	v_readlane_b32 s81, v255, 8
	v_readlane_b32 s84, v255, 11
	v_readlane_b32 s85, v255, 12
	v_readlane_b32 s86, v255, 13
	v_readlane_b32 s87, v255, 14
	v_readlane_b32 s88, v255, 15
	v_readlane_b32 s89, v255, 16
	v_readlane_b32 s90, v255, 17
	v_readlane_b32 s91, v255, 18
	v_readlane_b32 s92, v255, 19
	v_readlane_b32 s93, v255, 20
	v_readlane_b32 s94, v255, 21
	v_readlane_b32 s95, v255, 22
	s_waitcnt vmcnt(1)
	v_pk_mul_f32 v[70:71], v[26:27], v[32:33] op_sel_hi:[1,0]
	v_pk_mul_f32 v[72:73], v[24:25], v[32:33] op_sel_hi:[1,0]
	s_waitcnt vmcnt(0)
	v_pk_mul_f32 v[34:35], v[30:31], v[74:75] op_sel_hi:[1,0]
	v_pk_mul_f32 v[32:33], v[28:29], v[74:75] op_sel_hi:[1,0]
	s_cbranch_execnz .LBB0_94

; #define LAS __attribute__((address_space(3)))
; __device__ __forceinline__ unsigned pk2(float lo, float hi) { return f2bf(lo) | (f2bf(hi) << 16); }
; #define LDS_WAIT() asm volatile("s_waitcnt lgkmcnt(0)" ::: "memory")
; template <class RM> __device__ __forceinline__ void tr_item(const float* __restrict__ W, int K, int N, bf16* __restrict__ WT, RM rm, const float* ks0, const float* ks1, int ksplit, LAS float* scr, int item, int lane) {
;     const int nblk = N / 32, kb = item / nblk, nb = item % nblk, k0 = 64 * kb, n0 = 32 * nb;
;     f32x4 wv[8];
;     const int r8 = lane >> 3, cg = lane & 7;
; #pragma unroll
;     for (int i = 0; i < 8; ++i) wv[i] = *(const f32x4*)(W + (size_t)(k0 + 8 * i + r8) * N + n0 + 4 * cg);
;     const f32x4 cs = {rm.scale(n0 + 4 * cg), rm.scale(n0 + 4 * cg + 1), rm.scale(n0 + 4 * cg + 2), rm.scale(n0 + 4 * cg + 3)};
; #pragma unroll
;     for (int i = 0; i < 8; ++i) { const int kk = 8 * i + r8; f32x4 w = wv[i] * cs;
;         if (ks0) { const int k = k0 + kk; w = w * ((k < ksplit) ? ks0[k] : ks1[k - ksplit]); }
;         scr[kk * 33 + 4 * cg] = w[0]; scr[kk * 33 + 4 * cg + 1] = w[1]; scr[kk * 33 + 4 * cg + 2] = w[2]; scr[kk * 33 + 4 * cg + 3] = w[3]; }
;     LDS_WAIT(); asm volatile("" ::: "memory");
;     const int c = lane & 7;
; #pragma unroll
;     for (int j = 0; j < 4; ++j) { const int n = (lane >> 3) + 8 * j; const LAS float* s = scr + (8 * c) * 33 + n;
;         v4u o; o.x = pk2(s[0 * 33], s[1 * 33]); o.y = pk2(s[2 * 33], s[3 * 33]); o.z = pk2(s[4 * 33], s[5 * 33]); o.w = pk2(s[6 * 33], s[7 * 33]);
;         *(v4u*)(WT + (size_t)rm(n0 + n) * K + k0 + 8 * c) = o; }
.LBB0_121:
	s_andn2_b64 vcc, exec, s[0:1]
	s_cbranch_vccnz .LBB0_189
	s_add_i32 s0, s3, 0xdf00
	s_and_b32 s1, s0, 0xffff
	s_mulk_i32 s1, 0x1bad
	s_lshr_b32 s1, s1, 18
	s_mul_i32 s18, s1, 37
	s_sub_i32 s0, s0, s18
	s_lshl_b32 s59, s1, 6
	s_and_b32 s1, s59, 0xffc0
	s_lshl_b32 s18, s0, 5
	v_or_b32_e32 v2, s1, v76
	s_and_b32 s33, s18, 0xffe0
	s_lshl_b32 s18, s33, 2
	v_mul_u32_u24_e32 v2, 0x4a0, v2
	v_lshl_add_u64 v[0:1], v[50:51], 0, s[18:19]
	v_lshlrev_b32_e32 v36, 2, v2
	v_lshl_add_u64 v[28:29], v[0:1], 0, v[36:37]
	s_mov_b32 s1, 0x9000
	v_add_co_u32_e32 v4, vcc, s1, v28
	global_load_dwordx4 v[0:3], v[28:29], off nt
	s_nop 0
	v_addc_co_u32_e32 v5, vcc, 0, v29, vcc
	global_load_dwordx4 v[4:7], v[4:5], off offset:1024 nt
	v_add_co_u32_e32 v8, vcc, s51, v28
	s_mov_b32 s1, 0x1b000
	s_nop 0
	v_addc_co_u32_e32 v9, vcc, 0, v29, vcc
	global_load_dwordx4 v[8:11], v[8:9], off offset:2048 nt
	v_add_co_u32_e32 v12, vcc, s1, v28
	s_mov_b32 s1, 0x25000
	s_nop 0
	v_addc_co_u32_e32 v13, vcc, 0, v29, vcc
	global_load_dwordx4 v[12:15], v[12:13], off offset:3072 nt
	v_add_co_u32_e32 v16, vcc, s1, v28
	s_mov_b32 s1, 0x2e000
	s_nop 0
	v_addc_co_u32_e32 v17, vcc, 0, v29, vcc
	global_load_dwordx4 v[16:19], v[16:17], off nt
	v_add_co_u32_e32 v20, vcc, s1, v28
	s_mov_b32 s1, 0x37000
	s_nop 0
	v_addc_co_u32_e32 v21, vcc, 0, v29, vcc
	global_load_dwordx4 v[20:23], v[20:21], off offset:1024 nt
	v_add_co_u32_e32 v24, vcc, s1, v28
	s_mov_b32 s1, 0x40000
	s_nop 0
	v_addc_co_u32_e32 v25, vcc, 0, v29, vcc
	global_load_dwordx4 v[24:27], v[24:25], off offset:2048 nt
	v_add_co_u32_e32 v28, vcc, s1, v28
	v_add_u32_e32 v32, v78, v79
	s_nop 0
	v_addc_co_u32_e32 v29, vcc, 0, v29, vcc
	global_load_dwordx4 v[28:31], v[28:29], off offset:3072 nt
	s_and_b32 s58, s0, 0xffff
	s_cmp_gt_u32 s58, 7
	v_or_b32_e32 v36, s33, v76
	s_cselect_b64 s[64:65], -1, 0
	s_cmp_lt_u32 s58, 8
	s_waitcnt vmcnt(7)
	ds_write2_b32 v32, v0, v1 offset1:1
	ds_write2_b32 v32, v2, v3 offset0:2 offset1:3
	v_add_u32_e32 v0, 0x420, v32
	s_waitcnt vmcnt(6)
	ds_write2_b32 v0, v4, v5 offset1:1
	v_add_u32_e32 v0, 0x428, v32
	ds_write2_b32 v0, v6, v7 offset1:1
	v_add_u32_e32 v0, 0x840, v32
	s_waitcnt vmcnt(5)
	ds_write2_b32 v0, v8, v9 offset1:1
	v_add_u32_e32 v0, 0x848, v32
	ds_write2_b32 v0, v10, v11 offset1:1
	v_add_u32_e32 v0, 0xc60, v32
	s_waitcnt vmcnt(4)
	ds_write2_b32 v0, v12, v13 offset1:1
	v_add_u32_e32 v0, 0xc68, v32
	ds_write2_b32 v0, v14, v15 offset1:1
	v_add_u32_e32 v0, 0x1080, v32
	s_waitcnt vmcnt(3)
	ds_write2_b32 v0, v16, v17 offset1:1
	v_add_u32_e32 v0, 0x1088, v32
	ds_write2_b32 v0, v18, v19 offset1:1
	v_add_u32_e32 v0, 0x14a0, v32
	s_waitcnt vmcnt(2)
	ds_write2_b32 v0, v20, v21 offset1:1
	v_add_u32_e32 v0, 0x14a8, v32
	ds_write2_b32 v0, v22, v23 offset1:1
	v_add_u32_e32 v0, 0x18c0, v32
	s_waitcnt vmcnt(1)
	ds_write2_b32 v0, v24, v25 offset1:1
	v_add_u32_e32 v0, 0x18c8, v32
	ds_write2_b32 v0, v26, v27 offset1:1
	v_add_u32_e32 v0, 0x1ce0, v32
	s_waitcnt vmcnt(0)
	ds_write2_b32 v0, v28, v29 offset1:1
	v_add_u32_e32 v0, 0x1ce8, v32
	ds_write2_b32 v0, v30, v31 offset1:1
	s_waitcnt lgkmcnt(0)
	ds_read2_b32 v[8:9], v84 offset1:33
	ds_read2_b32 v[6:7], v84 offset0:66 offset1:99
	ds_read2_b32 v[4:5], v84 offset0:132 offset1:165
	ds_read2_b32 v[2:3], v84 offset0:198 offset1:231
	s_cbranch_scc1 .LBB0_137
	s_cmp_gt_u32 s58, 11
	s_mov_b64 s[0:1], -1
	s_cbranch_scc0 .LBB0_134
	s_cmp_eq_u32 s58, 12
	v_mov_b32_e32 v0, v87
	s_cbranch_scc1 .LBB0_133
	s_cmp_gt_u32 s58, 28
	s_cbranch_scc0 .LBB0_131
	s_cmp_gt_u32 s58, 32
	s_cbranch_scc0 .LBB0_128
	v_add_u32_e32 v0, 0xfffffbe0, v36
	v_lshlrev_b32_e32 v1, 2, v0
	v_lshrrev_b32_e32 v0, 1, v0
	v_and_b32_e32 v1, 0x80, v1
	v_and_b32_e32 v0, 0x7fffffe0, v0
	v_add3_u32 v0, v85, v0, v1
	s_mov_b64 s[0:1], 0

; #define LAS __attribute__((address_space(3)))
; __device__ __forceinline__ unsigned pk2(float lo, float hi) { return f2bf(lo) | (f2bf(hi) << 16); }
; #define LDS_WAIT() asm volatile("s_waitcnt lgkmcnt(0)" ::: "memory")
; template <class RM> __device__ __forceinline__ void tr_item(const float* __restrict__ W, int K, int N, bf16* __restrict__ WT, RM rm, const float* ks0, const float* ks1, int ksplit, LAS float* scr, int item, int lane) {
;     const int nblk = N / 32, kb = item / nblk, nb = item % nblk, k0 = 64 * kb, n0 = 32 * nb;
;     f32x4 wv[8];
;     const int r8 = lane >> 3, cg = lane & 7;
; #pragma unroll
;     for (int i = 0; i < 8; ++i) wv[i] = *(const f32x4*)(W + (size_t)(k0 + 8 * i + r8) * N + n0 + 4 * cg);
;     const f32x4 cs = {rm.scale(n0 + 4 * cg), rm.scale(n0 + 4 * cg + 1), rm.scale(n0 + 4 * cg + 2), rm.scale(n0 + 4 * cg + 3)};
; #pragma unroll
;     for (int i = 0; i < 8; ++i) { const int kk = 8 * i + r8; f32x4 w = wv[i] * cs;
;         if (ks0) { const int k = k0 + kk; w = w * ((k < ksplit) ? ks0[k] : ks1[k - ksplit]); }
;         scr[kk * 33 + 4 * cg] = w[0]; scr[kk * 33 + 4 * cg + 1] = w[1]; scr[kk * 33 + 4 * cg + 2] = w[2]; scr[kk * 33 + 4 * cg + 3] = w[3]; }
;     LDS_WAIT(); asm volatile("" ::: "memory");
;     const int c = lane & 7;
; #pragma unroll
;     for (int j = 0; j < 4; ++j) { const int n = (lane >> 3) + 8 * j; const LAS float* s = scr + (8 * c) * 33 + n;
;         v4u o; o.x = pk2(s[0 * 33], s[1 * 33]); o.y = pk2(s[2 * 33], s[3 * 33]); o.z = pk2(s[4 * 33], s[5 * 33]); o.w = pk2(s[6 * 33], s[7 * 33]);
;         *(v4u*)(WT + (size_t)rm(n0 + n) * K + k0 + 8 * c) = o; }
.LBB0_190:
	s_andn2_b64 vcc, exec, s[0:1]
	s_cbranch_vccnz .LBB0_192
	s_add_i32 s0, s39, 0x10e0
	s_and_b32 s1, s0, 0xfc0
	s_add_i32 s0, s9, 0xfffc9000
	s_and_b32 s0, s0, 0x3e0
	v_or_b32_e32 v2, s1, v76
	s_lshl_b32 s18, s0, 2
	v_lshl_add_u64 v[0:1], v[54:55], 0, s[18:19]
	v_lshlrev_b32_e32 v36, 12, v2
	v_lshl_add_u64 v[28:29], v[0:1], 0, v[36:37]
	v_add_co_u32_e32 v4, vcc, 0x8000, v28
	global_load_dwordx4 v[0:3], v[28:29], off nt
	s_nop 0
	v_addc_co_u32_e32 v5, vcc, 0, v29, vcc
	global_load_dwordx4 v[4:7], v[4:5], off nt
	v_add_co_u32_e32 v8, vcc, 0x10000, v28
	v_add_u32_e32 v32, v78, v79
	s_nop 0
	v_addc_co_u32_e32 v9, vcc, 0, v29, vcc
	global_load_dwordx4 v[8:11], v[8:9], off nt
	v_add_co_u32_e32 v12, vcc, 0x18000, v28
	s_lshl_b32 s18, s1, 1
	s_nop 0
	v_addc_co_u32_e32 v13, vcc, 0, v29, vcc
	global_load_dwordx4 v[12:15], v[12:13], off nt
	v_add_co_u32_e32 v16, vcc, 0x20000, v28
	s_nop 1
	v_addc_co_u32_e32 v17, vcc, 0, v29, vcc
	global_load_dwordx4 v[16:19], v[16:17], off nt
	v_add_co_u32_e32 v20, vcc, 0x28000, v28
	s_nop 1
	v_addc_co_u32_e32 v21, vcc, 0, v29, vcc
	global_load_dwordx4 v[20:23], v[20:21], off nt
	v_add_co_u32_e32 v24, vcc, 0x30000, v28
	s_nop 1
	v_addc_co_u32_e32 v25, vcc, 0, v29, vcc
	global_load_dwordx4 v[24:27], v[24:25], off nt
	v_add_co_u32_e32 v28, vcc, 0x38000, v28
	s_nop 1
	v_addc_co_u32_e32 v29, vcc, 0, v29, vcc
	global_load_dwordx4 v[28:31], v[28:29], off nt
	s_waitcnt vmcnt(7)
	ds_write2_b32 v32, v0, v1 offset1:1
	ds_write2_b32 v32, v2, v3 offset0:2 offset1:3
	v_add_u32_e32 v0, 0x420, v32
	s_waitcnt vmcnt(6)
	ds_write2_b32 v0, v4, v5 offset1:1
	v_add_u32_e32 v0, 0x428, v32
	ds_write2_b32 v0, v6, v7 offset1:1
	v_add_u32_e32 v0, 0x840, v32
	s_waitcnt vmcnt(5)
	ds_write2_b32 v0, v8, v9 offset1:1
	v_add_u32_e32 v0, 0x848, v32
	ds_write2_b32 v0, v10, v11 offset1:1
	v_add_u32_e32 v0, 0xc60, v32
	s_waitcnt vmcnt(4)
	ds_write2_b32 v0, v12, v13 offset1:1
	v_add_u32_e32 v0, 0xc68, v32
	ds_write2_b32 v0, v14, v15 offset1:1
	v_add_u32_e32 v0, 0x1080, v32
	s_waitcnt vmcnt(3)
	ds_write2_b32 v0, v16, v17 offset1:1
	v_add_u32_e32 v0, 0x1088, v32
	ds_write2_b32 v0, v18, v19 offset1:1
	v_add_u32_e32 v0, 0x14a0, v32
	s_waitcnt vmcnt(2)
	ds_write2_b32 v0, v20, v21 offset1:1
	v_add_u32_e32 v0, 0x14a8, v32
	ds_write2_b32 v0, v22, v23 offset1:1
	v_add_u32_e32 v0, 0x18c0, v32
	s_waitcnt vmcnt(1)
	ds_write2_b32 v0, v24, v25 offset1:1
	v_add_u32_e32 v0, 0x18c8, v32
	ds_write2_b32 v0, v26, v27 offset1:1
	v_add_u32_e32 v0, 0x1ce0, v32
	s_waitcnt vmcnt(0)
	ds_write2_b32 v0, v28, v29 offset1:1
	v_add_u32_e32 v0, 0x1ce8, v32
	ds_write2_b32 v0, v30, v31 offset1:1
	s_waitcnt lgkmcnt(0)
	ds_read2_b32 v[6:7], v84 offset0:33 offset1:41
	ds_read2_b32 v[8:9], v84 offset1:8
	ds_read2_b32 v[10:11], v84 offset0:66 offset1:74
	ds_read2_b32 v[12:13], v84 offset0:99 offset1:107
	ds_read2_b32 v[14:15], v84 offset0:132 offset1:140
	ds_read2_b32 v[16:17], v84 offset0:165 offset1:173
	ds_read2_b32 v[18:19], v84 offset0:198 offset1:206
	ds_read2_b32 v[20:21], v84 offset0:231 offset1:239
	s_waitcnt lgkmcnt(7)
	v_bfe_u32 v3, v6, 16, 1
	s_waitcnt lgkmcnt(6)
	v_bfe_u32 v2, v8, 16, 1
	v_add3_u32 v2, v8, v2, s49
	v_lshrrev_b32_e32 v2, 16, v2
	v_add3_u32 v3, v6, v3, s49
	v_and_or_b32 v2, v3, s50, v2
	s_waitcnt lgkmcnt(5)
	v_bfe_u32 v3, v10, 16, 1
	v_add3_u32 v3, v10, v3, s49
	s_waitcnt lgkmcnt(4)
	v_bfe_u32 v4, v12, 16, 1
	v_lshrrev_b32_e32 v3, 16, v3
	v_add3_u32 v4, v12, v4, s49
	v_and_or_b32 v3, v4, s50, v3
	s_waitcnt lgkmcnt(3)
	v_bfe_u32 v4, v14, 16, 1
	v_add3_u32 v4, v14, v4, s49
	s_waitcnt lgkmcnt(2)
	v_bfe_u32 v5, v16, 16, 1
	v_lshrrev_b32_e32 v4, 16, v4
	v_add3_u32 v5, v16, v5, s49
	v_and_or_b32 v4, v5, s50, v4
	s_waitcnt lgkmcnt(1)
; #define LAS __attribute__((address_space(3)))
; __device__ __forceinline__ unsigned pk2(float lo, float hi) { return f2bf(lo) | (f2bf(hi) << 16); }
; #define LDS_WAIT() asm volatile("s_waitcnt lgkmcnt(0)" ::: "memory")
; template <class RM> __device__ __forceinline__ void tr_item(const float* __restrict__ W, int K, int N, bf16* __restrict__ WT, RM rm, const float* ks0, const float* ks1, int ksplit, LAS float* scr, int item, int lane) {
;     ...
;     for (int j = 0; j < 4; ++j) { const int n = (lane >> 3) + 8 * j; const LAS float* s = scr + (8 * c) * 33 + n;
;         v4u o; o.x = pk2(s[0 * 33], s[1 * 33]); o.y = pk2(s[2 * 33], s[3 * 33]); o.z = pk2(s[4 * 33], s[5 * 33]); o.w = pk2(s[6 * 33], s[7 * 33]);
;         *(v4u*)(WT + (size_t)rm(n0 + n) * K + k0 + 8 * c) = o; }
;     LDS_WAIT(); asm volatile("" ::: "memory");
	v_bfe_u32 v5, v18, 16, 1
	v_add3_u32 v5, v18, v5, s49
	s_waitcnt lgkmcnt(0)
	v_bfe_u32 v6, v20, 16, 1
	v_lshrrev_b32_e32 v5, 16, v5
	v_add3_u32 v6, v20, v6, s49
	v_and_or_b32 v5, v6, s50, v5
	v_or_b32_e32 v6, s0, v76
	v_mul_u32_u24_e32 v6, 0xb00, v6
	v_lshl_add_u64 v[0:1], v[56:57], 0, s[18:19]
	v_lshlrev_b32_e32 v36, 1, v6
	v_lshl_add_u64 v[22:23], v[0:1], 0, v[36:37]
	global_store_dwordx4 v[22:23], v[2:5], off
	v_bfe_u32 v6, v21, 16, 1
	v_add3_u32 v6, v21, v6, s49
	v_bfe_u32 v2, v9, 16, 1
	v_add3_u32 v2, v9, v2, s49
	v_bfe_u32 v3, v7, 16, 1
	v_lshrrev_b32_e32 v2, 16, v2
	v_add3_u32 v3, v7, v3, s49
	v_and_or_b32 v2, v3, s50, v2
	v_bfe_u32 v3, v11, 16, 1
	v_add3_u32 v3, v11, v3, s49
	v_bfe_u32 v4, v13, 16, 1
	v_lshrrev_b32_e32 v3, 16, v3
	v_add3_u32 v4, v13, v4, s49
	v_and_or_b32 v3, v4, s50, v3
	v_bfe_u32 v4, v15, 16, 1
	v_add3_u32 v4, v15, v4, s49
	v_bfe_u32 v5, v17, 16, 1
	v_lshrrev_b32_e32 v4, 16, v4
	v_add3_u32 v5, v17, v5, s49
	v_and_or_b32 v4, v5, s50, v4
	v_bfe_u32 v5, v19, 16, 1
	v_add3_u32 v5, v19, v5, s49
	v_lshrrev_b32_e32 v5, 16, v5
	v_and_or_b32 v5, v6, s50, v5
	v_or_b32_e32 v6, s0, v80
	v_mul_u32_u24_e32 v6, 0xb00, v6
	v_lshlrev_b32_e32 v36, 1, v6
	v_lshl_add_u64 v[6:7], v[0:1], 0, v[36:37]
	global_store_dwordx4 v[6:7], v[2:5], off
	ds_read2_b32 v[6:7], v84 offset0:16 offset1:24
	ds_read2_b32 v[8:9], v84 offset0:49 offset1:57
	ds_read2_b32 v[10:11], v84 offset0:82 offset1:90
	ds_read2_b32 v[12:13], v84 offset0:115 offset1:123
	ds_read2_b32 v[14:15], v84 offset0:148 offset1:156
	ds_read2_b32 v[16:17], v84 offset0:181 offset1:189
	ds_read2_b32 v[18:19], v84 offset0:214 offset1:222
	ds_read2_b32 v[20:21], v84 offset0:247 offset1:255
	s_waitcnt lgkmcnt(7)
	v_bfe_u32 v2, v6, 16, 1
	v_add3_u32 v2, v6, v2, s49
	s_waitcnt lgkmcnt(6)
	v_bfe_u32 v3, v8, 16, 1
	v_lshrrev_b32_e32 v2, 16, v2
	v_add3_u32 v3, v8, v3, s49
	v_and_or_b32 v2, v3, s50, v2
	s_waitcnt lgkmcnt(5)
	v_bfe_u32 v3, v10, 16, 1
	v_add3_u32 v3, v10, v3, s49
	s_waitcnt lgkmcnt(4)
	v_bfe_u32 v4, v12, 16, 1
	v_lshrrev_b32_e32 v3, 16, v3
	v_add3_u32 v4, v12, v4, s49
	v_and_or_b32 v3, v4, s50, v3
	s_waitcnt lgkmcnt(3)
	v_bfe_u32 v4, v14, 16, 1
	v_add3_u32 v4, v14, v4, s49
	s_waitcnt lgkmcnt(2)
	v_bfe_u32 v5, v16, 16, 1
	v_lshrrev_b32_e32 v4, 16, v4
	v_add3_u32 v5, v16, v5, s49
	v_and_or_b32 v4, v5, s50, v4
	s_waitcnt lgkmcnt(1)
	v_bfe_u32 v5, v18, 16, 1
	v_add3_u32 v5, v18, v5, s49
	s_waitcnt lgkmcnt(0)
	v_bfe_u32 v6, v20, 16, 1
	v_lshrrev_b32_e32 v5, 16, v5
	v_add3_u32 v6, v20, v6, s49
	v_and_or_b32 v5, v6, s50, v5
	v_or_b32_e32 v6, s0, v81
	v_mul_u32_u24_e32 v6, 0xb00, v6
	v_lshlrev_b32_e32 v36, 1, v6
	v_lshl_add_u64 v[22:23], v[0:1], 0, v[36:37]
	global_store_dwordx4 v[22:23], v[2:5], off
	v_bfe_u32 v6, v21, 16, 1
	v_add3_u32 v6, v21, v6, s49
	v_bfe_u32 v2, v7, 16, 1
	v_add3_u32 v2, v7, v2, s49
	v_bfe_u32 v3, v9, 16, 1
	v_lshrrev_b32_e32 v2, 16, v2
	v_add3_u32 v3, v9, v3, s49
	v_and_or_b32 v2, v3, s50, v2
	v_bfe_u32 v3, v11, 16, 1
	v_add3_u32 v3, v11, v3, s49
	v_bfe_u32 v4, v13, 16, 1
	v_lshrrev_b32_e32 v3, 16, v3
	v_add3_u32 v4, v13, v4, s49
	v_and_or_b32 v3, v4, s50, v3
	v_bfe_u32 v4, v15, 16, 1
	v_add3_u32 v4, v15, v4, s49
	v_bfe_u32 v5, v17, 16, 1
	v_lshrrev_b32_e32 v4, 16, v4
	v_add3_u32 v5, v17, v5, s49
	v_and_or_b32 v4, v5, s50, v4
	v_bfe_u32 v5, v19, 16, 1
	v_add3_u32 v5, v19, v5, s49
	v_lshrrev_b32_e32 v5, 16, v5
	v_and_or_b32 v5, v6, s50, v5
	v_or_b32_e32 v6, s0, v83
	v_mul_u32_u24_e32 v6, 0xb00, v6
	v_lshlrev_b32_e32 v36, 1, v6
	v_lshl_add_u64 v[0:1], v[0:1], 0, v[36:37]
	global_store_dwordx4 v[0:1], v[2:5], off
	s_waitcnt lgkmcnt(0)

; #define LAS __attribute__((address_space(3)))
; __device__ __forceinline__ unsigned pk2(float lo, float hi) { return f2bf(lo) | (f2bf(hi) << 16); }
; #define LDS_WAIT() asm volatile("s_waitcnt lgkmcnt(0)" ::: "memory")
; template <class RM> __device__ __forceinline__ void tr_item(const float* __restrict__ W, int K, int N, bf16* __restrict__ WT, RM rm, const float* ks0, const float* ks1, int ksplit, LAS float* scr, int item, int lane) {
;     const int nblk = N / 32, kb = item / nblk, nb = item % nblk, k0 = 64 * kb, n0 = 32 * nb;
;     f32x4 wv[8];
;     const int r8 = lane >> 3, cg = lane & 7;
; #pragma unroll
;     for (int i = 0; i < 8; ++i) wv[i] = *(const f32x4*)(W + (size_t)(k0 + 8 * i + r8) * N + n0 + 4 * cg);
;     const f32x4 cs = {rm.scale(n0 + 4 * cg), rm.scale(n0 + 4 * cg + 1), rm.scale(n0 + 4 * cg + 2), rm.scale(n0 + 4 * cg + 3)};
; #pragma unroll
;     for (int i = 0; i < 8; ++i) { const int kk = 8 * i + r8; f32x4 w = wv[i] * cs;
;         if (ks0) { const int k = k0 + kk; w = w * ((k < ksplit) ? ks0[k] : ks1[k - ksplit]); }
;         scr[kk * 33 + 4 * cg] = w[0]; scr[kk * 33 + 4 * cg + 1] = w[1]; scr[kk * 33 + 4 * cg + 2] = w[2]; scr[kk * 33 + 4 * cg + 3] = w[3]; }
;     LDS_WAIT(); asm volatile("" ::: "memory");
;     const int c = lane & 7;
; #pragma unroll
;     for (int j = 0; j < 4; ++j) { const int n = (lane >> 3) + 8 * j; const LAS float* s = scr + (8 * c) * 33 + n;
;         v4u o; o.x = pk2(s[0 * 33], s[1 * 33]); o.y = pk2(s[2 * 33], s[3 * 33]); o.z = pk2(s[4 * 33], s[5 * 33]); o.w = pk2(s[6 * 33], s[7 * 33]);
;         *(v4u*)(WT + (size_t)rm(n0 + n) * K + k0 + 8 * c) = o; }
.LBB0_193:
	s_andn2_b64 vcc, exec, s[0:1]
	s_cbranch_vccnz .LBB0_195
	s_add_i32 s0, s3, 0xef80
	s_and_b32 s1, s0, 0xffff
	s_mul_i32 s1, s1, 0xba2f
	s_lshr_b32 s1, s1, 23
	s_mul_i32 s18, s1, 0xb0
	s_sub_i32 s0, s0, s18
	s_lshl_b32 s18, s0, 5
	s_and_b32 s33, s18, 0xffe0
	v_lshl_or_b32 v2, s1, 6, v76
	s_lshl_b32 s18, s33, 2
	v_lshl_add_u64 v[0:1], v[58:59], 0, s[18:19]
	v_mul_u32_u24_e32 v36, 0x5800, v2
	v_lshl_add_u64 v[4:5], v[0:1], 0, v[36:37]
	s_mov_b32 s18, 0x2c000
	v_add_co_u32_e32 v0, vcc, s18, v4
	global_load_dwordx4 v[10:13], v[4:5], off nt
	s_nop 0
	v_addc_co_u32_e32 v1, vcc, 0, v5, vcc
	s_mov_b32 s18, 0x58000
	global_load_dwordx4 v[14:17], v[0:1], off nt
	v_add_co_u32_e32 v0, vcc, s18, v4
	s_mov_b32 s18, 0x84000
	s_nop 0
	v_addc_co_u32_e32 v1, vcc, 0, v5, vcc
	global_load_dwordx4 v[18:21], v[0:1], off nt
	v_add_co_u32_e32 v0, vcc, s18, v4
	s_mov_b32 s18, 0xb0000
	s_nop 0
	v_addc_co_u32_e32 v1, vcc, 0, v5, vcc
	global_load_dwordx4 v[22:25], v[0:1], off nt
	v_add_co_u32_e32 v0, vcc, s18, v4
	s_mov_b32 s18, 0xdc000
	s_nop 0
	v_addc_co_u32_e32 v1, vcc, 0, v5, vcc
	global_load_dwordx4 v[26:29], v[0:1], off nt
	v_add_co_u32_e32 v0, vcc, s18, v4
	s_mov_b32 s18, 0x108000
	s_nop 0
	v_addc_co_u32_e32 v1, vcc, 0, v5, vcc
	global_load_dwordx4 v[30:33], v[0:1], off nt
	v_add_co_u32_e32 v0, vcc, s18, v4
	s_mov_b32 s18, 0x134000
	s_nop 0
	v_addc_co_u32_e32 v1, vcc, 0, v5, vcc
	global_load_dwordx4 v[0:3], v[0:1], off nt
	v_add_co_u32_e32 v4, vcc, s18, v4
	s_and_b32 s0, s0, 0xffff
	s_nop 0
	v_addc_co_u32_e32 v5, vcc, 0, v5, vcc
	global_load_dwordx4 v[4:7], v[4:5], off nt
	s_lshl_b32 s18, s1, 7
	v_or_b32_e32 v9, s33, v77
	s_cmpk_gt_u32 s0, 0x57
	s_cselect_b64 vcc, -1, 0
	v_cmp_lt_u32_e64 s[0:1], s69, v9
	v_cndmask_b32_e32 v8, v96, v97, vcc
	v_add_u32_e32 v34, v78, v79
	v_cndmask_b32_e64 v9, v96, v97, s[0:1]
	s_and_b64 s[0:1], vcc, exec
	s_cselect_b32 s0, 0x80, 0
	s_waitcnt vmcnt(7)
	v_pk_mul_f32 v[12:13], v[8:9], v[12:13] op_sel_hi:[0,1]
	v_pk_mul_f32 v[10:11], v[8:9], v[10:11]
	ds_write2_b32 v34, v10, v11 offset1:1
	ds_write2_b32 v34, v12, v13 offset0:2 offset1:3
	s_waitcnt vmcnt(6)
	v_pk_mul_f32 v[12:13], v[8:9], v[14:15]
	v_add_u32_e32 v14, 0x420, v34
	v_pk_mul_f32 v[10:11], v[8:9], v[16:17] op_sel_hi:[0,1]
	ds_write2_b32 v14, v12, v13 offset1:1
	v_add_u32_e32 v12, 0x428, v34
	ds_write2_b32 v12, v10, v11 offset1:1
	s_waitcnt vmcnt(5)
	v_pk_mul_f32 v[12:13], v[8:9], v[18:19]
	v_add_u32_e32 v14, 0x840, v34
	v_pk_mul_f32 v[10:11], v[8:9], v[20:21] op_sel_hi:[0,1]
	ds_write2_b32 v14, v12, v13 offset1:1
	v_add_u32_e32 v12, 0x848, v34
	ds_write2_b32 v12, v10, v11 offset1:1
	s_waitcnt vmcnt(4)
	v_pk_mul_f32 v[12:13], v[8:9], v[22:23]
	v_add_u32_e32 v14, 0xc60, v34
	v_pk_mul_f32 v[10:11], v[8:9], v[24:25] op_sel_hi:[0,1]
	ds_write2_b32 v14, v12, v13 offset1:1
	v_add_u32_e32 v12, 0xc68, v34
	ds_write2_b32 v12, v10, v11 offset1:1
	s_waitcnt vmcnt(3)
	v_pk_mul_f32 v[12:13], v[8:9], v[26:27]
	v_add_u32_e32 v14, 0x1080, v34
	v_pk_mul_f32 v[10:11], v[8:9], v[28:29] op_sel_hi:[0,1]
	ds_write2_b32 v14, v12, v13 offset1:1
	v_add_u32_e32 v12, 0x1088, v34
	ds_write2_b32 v12, v10, v11 offset1:1
	s_waitcnt vmcnt(2)
	v_pk_mul_f32 v[12:13], v[8:9], v[30:31]
	v_add_u32_e32 v14, 0x14a0, v34
	v_pk_mul_f32 v[10:11], v[8:9], v[32:33] op_sel_hi:[0,1]
	ds_write2_b32 v14, v12, v13 offset1:1
	v_add_u32_e32 v12, 0x14a8, v34
	ds_write2_b32 v12, v10, v11 offset1:1
	s_waitcnt vmcnt(1)
	v_pk_mul_f32 v[0:1], v[8:9], v[0:1]
	v_add_u32_e32 v10, 0x18c0, v34
	v_pk_mul_f32 v[2:3], v[8:9], v[2:3] op_sel_hi:[0,1]
	ds_write2_b32 v10, v0, v1 offset1:1
	v_add_u32_e32 v0, 0x18c8, v34
	ds_write2_b32 v0, v2, v3 offset1:1
	s_waitcnt vmcnt(0)
	v_pk_mul_f32 v[2:3], v[8:9], v[4:5]
	v_add_u32_e32 v4, 0x1ce0, v34
	v_pk_mul_f32 v[0:1], v[8:9], v[6:7] op_sel_hi:[0,1]
	ds_write2_b32 v4, v2, v3 offset1:1
	v_add_u32_e32 v2, 0x1ce8, v34
	ds_write2_b32 v2, v0, v1 offset1:1
	s_waitcnt lgkmcnt(0)
	ds_read2_b32 v[6:7], v84 offset0:33 offset1:41
	ds_read2_b32 v[8:9], v84 offset1:8
	ds_read2_b32 v[10:11], v84 offset0:66 offset1:74
	ds_read2_b32 v[12:13], v84 offset0:99 offset1:107
	ds_read2_b32 v[14:15], v84 offset0:132 offset1:140
	ds_read2_b32 v[16:17], v84 offset0:165 offset1:173
	ds_read2_b32 v[18:19], v84 offset0:198 offset1:206
	ds_read2_b32 v[20:21], v84 offset0:231 offset1:239
	s_waitcnt lgkmcnt(7)
	v_bfe_u32 v3, v6, 16, 1
	s_waitcnt lgkmcnt(6)
	v_bfe_u32 v2, v8, 16, 1
	v_add3_u32 v2, v8, v2, s49
	v_lshrrev_b32_e32 v2, 16, v2
	v_add3_u32 v3, v6, v3, s49
	v_and_or_b32 v2, v3, s50, v2
	s_waitcnt lgkmcnt(5)
	v_bfe_u32 v3, v10, 16, 1
	v_add3_u32 v3, v10, v3, s49
	s_waitcnt lgkmcnt(4)
; #define LAS __attribute__((address_space(3)))
; __device__ __forceinline__ unsigned pk2(float lo, float hi) { return f2bf(lo) | (f2bf(hi) << 16); }
; #define LDS_WAIT() asm volatile("s_waitcnt lgkmcnt(0)" ::: "memory")
; template <class RM> __device__ __forceinline__ void tr_item(const float* __restrict__ W, int K, int N, bf16* __restrict__ WT, RM rm, const float* ks0, const float* ks1, int ksplit, LAS float* scr, int item, int lane) {
;     ...
;     for (int j = 0; j < 4; ++j) { const int n = (lane >> 3) + 8 * j; const LAS float* s = scr + (8 * c) * 33 + n;
;         v4u o; o.x = pk2(s[0 * 33], s[1 * 33]); o.y = pk2(s[2 * 33], s[3 * 33]); o.z = pk2(s[4 * 33], s[5 * 33]); o.w = pk2(s[6 * 33], s[7 * 33]);
;         *(v4u*)(WT + (size_t)rm(n0 + n) * K + k0 + 8 * c) = o; }
;     LDS_WAIT(); asm volatile("" ::: "memory");
	v_bfe_u32 v4, v12, 16, 1
	v_lshrrev_b32_e32 v3, 16, v3
	v_add3_u32 v4, v12, v4, s49
	v_and_or_b32 v3, v4, s50, v3
	s_waitcnt lgkmcnt(3)
	v_bfe_u32 v4, v14, 16, 1
	v_add3_u32 v4, v14, v4, s49
	s_waitcnt lgkmcnt(2)
	v_bfe_u32 v5, v16, 16, 1
	v_lshrrev_b32_e32 v4, 16, v4
	v_add3_u32 v5, v16, v5, s49
	v_and_or_b32 v4, v5, s50, v4
	s_waitcnt lgkmcnt(1)
	v_bfe_u32 v5, v18, 16, 1
	v_add3_u32 v5, v18, v5, s49
	s_waitcnt lgkmcnt(0)
	v_bfe_u32 v6, v20, 16, 1
	v_lshrrev_b32_e32 v5, 16, v5
	v_add3_u32 v6, v20, v6, s49
	v_and_or_b32 v5, v6, s50, v5
	v_or_b32_e32 v6, s33, v76
	v_add_u32_e32 v8, 0xfffff500, v6
	v_cndmask_b32_e32 v6, v6, v8, vcc
	v_lshlrev_b32_e32 v8, 1, v6
	v_and_b32_e32 v8, 0xffffff00, v8
	v_and_b32_e32 v6, 0x67, v6
	v_or3_b32 v22, v6, v8, s0
	v_ashrrev_i32_e32 v23, 31, v22
	v_lshl_add_u64 v[0:1], v[60:61], 0, s[18:19]
	v_lshlrev_b64 v[22:23], 11, v[22:23]
	v_lshl_add_u64 v[22:23], v[0:1], 0, v[22:23]
	global_store_dwordx4 v[22:23], v[2:5], off
	v_bfe_u32 v6, v21, 16, 1
	v_add3_u32 v6, v21, v6, s49
	v_bfe_u32 v2, v9, 16, 1
	v_add3_u32 v2, v9, v2, s49
	v_bfe_u32 v3, v7, 16, 1
	v_lshrrev_b32_e32 v2, 16, v2
	v_add3_u32 v3, v7, v3, s49
	v_and_or_b32 v2, v3, s50, v2
	v_bfe_u32 v3, v11, 16, 1
	v_add3_u32 v3, v11, v3, s49
	v_bfe_u32 v4, v13, 16, 1
	v_lshrrev_b32_e32 v3, 16, v3
	v_add3_u32 v4, v13, v4, s49
	v_and_or_b32 v3, v4, s50, v3
	v_bfe_u32 v4, v15, 16, 1
	v_add3_u32 v4, v15, v4, s49
	v_bfe_u32 v5, v17, 16, 1
	v_lshrrev_b32_e32 v4, 16, v4
	v_add3_u32 v5, v17, v5, s49
	v_and_or_b32 v4, v5, s50, v4
	v_bfe_u32 v5, v19, 16, 1
	v_add3_u32 v5, v19, v5, s49
	v_lshrrev_b32_e32 v5, 16, v5
	v_and_or_b32 v5, v6, s50, v5
	v_or_b32_e32 v6, s33, v80
	v_add_u32_e32 v7, 0xfffff500, v6
	v_cndmask_b32_e32 v6, v6, v7, vcc
	v_lshlrev_b32_e32 v7, 1, v6
	v_and_b32_e32 v7, 0xffffff00, v7
	v_and_b32_e32 v6, 0x6f, v6
	v_or3_b32 v6, v6, v7, s0
	v_ashrrev_i32_e32 v7, 31, v6
	v_lshlrev_b64 v[6:7], 11, v[6:7]
	v_lshl_add_u64 v[6:7], v[0:1], 0, v[6:7]
	global_store_dwordx4 v[6:7], v[2:5], off
	ds_read2_b32 v[6:7], v84 offset0:16 offset1:24
	ds_read2_b32 v[8:9], v84 offset0:49 offset1:57
	ds_read2_b32 v[10:11], v84 offset0:82 offset1:90
	ds_read2_b32 v[12:13], v84 offset0:115 offset1:123
	ds_read2_b32 v[14:15], v84 offset0:148 offset1:156
	ds_read2_b32 v[16:17], v84 offset0:181 offset1:189
	ds_read2_b32 v[18:19], v84 offset0:214 offset1:222
	ds_read2_b32 v[20:21], v84 offset0:247 offset1:255
	s_waitcnt lgkmcnt(7)
	v_bfe_u32 v2, v6, 16, 1
	v_add3_u32 v2, v6, v2, s49
	s_waitcnt lgkmcnt(6)
	v_bfe_u32 v3, v8, 16, 1
	v_lshrrev_b32_e32 v2, 16, v2
	v_add3_u32 v3, v8, v3, s49
	v_and_or_b32 v2, v3, s50, v2
	s_waitcnt lgkmcnt(5)
	v_bfe_u32 v3, v10, 16, 1
	v_add3_u32 v3, v10, v3, s49
	s_waitcnt lgkmcnt(4)
	v_bfe_u32 v4, v12, 16, 1
	v_lshrrev_b32_e32 v3, 16, v3
	v_add3_u32 v4, v12, v4, s49
	v_and_or_b32 v3, v4, s50, v3
	s_waitcnt lgkmcnt(3)
	v_bfe_u32 v4, v14, 16, 1
	v_add3_u32 v4, v14, v4, s49
	s_waitcnt lgkmcnt(2)
	v_bfe_u32 v5, v16, 16, 1
	v_lshrrev_b32_e32 v4, 16, v4
	v_add3_u32 v5, v16, v5, s49
	v_and_or_b32 v4, v5, s50, v4
	s_waitcnt lgkmcnt(1)
	v_bfe_u32 v5, v18, 16, 1
	v_add3_u32 v5, v18, v5, s49
	s_waitcnt lgkmcnt(0)
	v_bfe_u32 v6, v20, 16, 1
	v_lshrrev_b32_e32 v5, 16, v5
	v_add3_u32 v6, v20, v6, s49
	v_and_or_b32 v5, v6, s50, v5
	v_or_b32_e32 v6, s33, v81
	v_add_u32_e32 v8, 0xfffff500, v6
	v_cndmask_b32_e32 v6, v6, v8, vcc
	v_lshlrev_b32_e32 v8, 1, v6
	v_and_b32_e32 v8, 0xffffff00, v8
	v_and_b32_e32 v6, 0x77, v6
	v_or3_b32 v22, v6, v8, s0
	v_ashrrev_i32_e32 v23, 31, v22
	v_lshlrev_b64 v[22:23], 11, v[22:23]
	v_lshl_add_u64 v[22:23], v[0:1], 0, v[22:23]
	global_store_dwordx4 v[22:23], v[2:5], off
	v_bfe_u32 v6, v21, 16, 1
	v_add3_u32 v6, v21, v6, s49
	v_bfe_u32 v2, v7, 16, 1
	v_add3_u32 v2, v7, v2, s49
	v_bfe_u32 v3, v9, 16, 1
	v_lshrrev_b32_e32 v2, 16, v2
	v_add3_u32 v3, v9, v3, s49
	v_and_or_b32 v2, v3, s50, v2
	v_bfe_u32 v3, v11, 16, 1
	v_add3_u32 v3, v11, v3, s49
	v_bfe_u32 v4, v13, 16, 1
	v_lshrrev_b32_e32 v3, 16, v3
	v_add3_u32 v4, v13, v4, s49
	v_and_or_b32 v3, v4, s50, v3
	v_bfe_u32 v4, v15, 16, 1
	v_add3_u32 v4, v15, v4, s49
	v_bfe_u32 v5, v17, 16, 1
	v_lshrrev_b32_e32 v4, 16, v4
	v_add3_u32 v5, v17, v5, s49
	v_and_or_b32 v4, v5, s50, v4
	v_bfe_u32 v5, v19, 16, 1
	v_add3_u32 v5, v19, v5, s49
	v_lshrrev_b32_e32 v5, 16, v5
	v_and_or_b32 v5, v6, s50, v5
	v_or_b32_e32 v6, s33, v83
	v_add_u32_e32 v7, 0xfffff500, v6
	v_cndmask_b32_e32 v6, v6, v7, vcc
	v_lshlrev_b32_e32 v7, 1, v6
	v_and_b32_e32 v7, 0xffffff00, v7
	v_and_b32_e32 v6, 0x7f, v6
	v_or3_b32 v6, v6, v7, s0
	v_ashrrev_i32_e32 v7, 31, v6
	v_lshlrev_b64 v[6:7], 11, v[6:7]
	v_lshl_add_u64 v[0:1], v[0:1], 0, v[6:7]
	global_store_dwordx4 v[0:1], v[2:5], off
	s_waitcnt lgkmcnt(0)

; #define LAS __attribute__((address_space(3)))
; __device__ __forceinline__ unsigned pk2(float lo, float hi) { return f2bf(lo) | (f2bf(hi) << 16); }
; #define LDS_WAIT() asm volatile("s_waitcnt lgkmcnt(0)" ::: "memory")
; template <class RM> __device__ __forceinline__ void tr_item(const float* __restrict__ W, int K, int N, bf16* __restrict__ WT, RM rm, const float* ks0, const float* ks1, int ksplit, LAS float* scr, int item, int lane) {
;     const int nblk = N / 32, kb = item / nblk, nb = item % nblk, k0 = 64 * kb, n0 = 32 * nb;
;     f32x4 wv[8];
;     const int r8 = lane >> 3, cg = lane & 7;
; #pragma unroll
;     for (int i = 0; i < 8; ++i) wv[i] = *(const f32x4*)(W + (size_t)(k0 + 8 * i + r8) * N + n0 + 4 * cg);
;     const f32x4 cs = {rm.scale(n0 + 4 * cg), rm.scale(n0 + 4 * cg + 1), rm.scale(n0 + 4 * cg + 2), rm.scale(n0 + 4 * cg + 3)};
; #pragma unroll
;     for (int i = 0; i < 8; ++i) { const int kk = 8 * i + r8; f32x4 w = wv[i] * cs;
;         if (ks0) { const int k = k0 + kk; w = w * ((k < ksplit) ? ks0[k] : ks1[k - ksplit]); }
;         scr[kk * 33 + 4 * cg] = w[0]; scr[kk * 33 + 4 * cg + 1] = w[1]; scr[kk * 33 + 4 * cg + 2] = w[2]; scr[kk * 33 + 4 * cg + 3] = w[3]; }
;     LDS_WAIT(); asm volatile("" ::: "memory");
;     const int c = lane & 7;
; #pragma unroll
;     for (int j = 0; j < 4; ++j) { const int n = (lane >> 3) + 8 * j; const LAS float* s = scr + (8 * c) * 33 + n;
;         v4u o; o.x = pk2(s[0 * 33], s[1 * 33]); o.y = pk2(s[2 * 33], s[3 * 33]); o.z = pk2(s[4 * 33], s[5 * 33]); o.w = pk2(s[6 * 33], s[7 * 33]);
;         *(v4u*)(WT + (size_t)rm(n0 + n) * K + k0 + 8 * c) = o; }
.LBB0_196:
	s_andn2_b64 vcc, exec, s[0:1]
	s_cbranch_vccnz .LBB0_198
	s_add_i32 s0, s39, 0x31e0
	s_and_b32 s1, s0, 0xfc0
	s_add_i32 s0, s9, 0xfffea000
	s_and_b32 s0, s0, 0x3e0
	v_or_b32_e32 v2, s1, v76
	s_lshl_b32 s18, s0, 2
	v_lshl_add_u64 v[0:1], v[62:63], 0, s[18:19]
	v_lshlrev_b32_e32 v36, 12, v2
	v_lshl_add_u64 v[28:29], v[0:1], 0, v[36:37]
	v_add_co_u32_e32 v4, vcc, 0x8000, v28
	global_load_dwordx4 v[0:3], v[28:29], off nt
	s_nop 0
	v_addc_co_u32_e32 v5, vcc, 0, v29, vcc
	global_load_dwordx4 v[4:7], v[4:5], off nt
	v_add_co_u32_e32 v8, vcc, 0x10000, v28
	v_add_u32_e32 v32, v78, v79
	s_nop 0
	v_addc_co_u32_e32 v9, vcc, 0, v29, vcc
	global_load_dwordx4 v[8:11], v[8:9], off nt
	v_add_co_u32_e32 v12, vcc, 0x18000, v28
	s_lshl_b32 s18, s1, 1
	s_nop 0
	v_addc_co_u32_e32 v13, vcc, 0, v29, vcc
	global_load_dwordx4 v[12:15], v[12:13], off nt
	v_add_co_u32_e32 v16, vcc, 0x20000, v28
	s_nop 1
	v_addc_co_u32_e32 v17, vcc, 0, v29, vcc
	global_load_dwordx4 v[16:19], v[16:17], off nt
	v_add_co_u32_e32 v20, vcc, 0x28000, v28
	s_nop 1
	v_addc_co_u32_e32 v21, vcc, 0, v29, vcc
	global_load_dwordx4 v[20:23], v[20:21], off nt
	v_add_co_u32_e32 v24, vcc, 0x30000, v28
	s_nop 1
	v_addc_co_u32_e32 v25, vcc, 0, v29, vcc
	global_load_dwordx4 v[24:27], v[24:25], off nt
	v_add_co_u32_e32 v28, vcc, 0x38000, v28
	s_nop 1
	v_addc_co_u32_e32 v29, vcc, 0, v29, vcc
	global_load_dwordx4 v[28:31], v[28:29], off nt
	s_waitcnt vmcnt(7)
	ds_write2_b32 v32, v0, v1 offset1:1
	ds_write2_b32 v32, v2, v3 offset0:2 offset1:3
	v_add_u32_e32 v0, 0x420, v32
	s_waitcnt vmcnt(6)
	ds_write2_b32 v0, v4, v5 offset1:1
	v_add_u32_e32 v0, 0x428, v32
	ds_write2_b32 v0, v6, v7 offset1:1
	v_add_u32_e32 v0, 0x840, v32
	s_waitcnt vmcnt(5)
	ds_write2_b32 v0, v8, v9 offset1:1
	v_add_u32_e32 v0, 0x848, v32
	ds_write2_b32 v0, v10, v11 offset1:1
	v_add_u32_e32 v0, 0xc60, v32
	s_waitcnt vmcnt(4)
	ds_write2_b32 v0, v12, v13 offset1:1
	v_add_u32_e32 v0, 0xc68, v32
	ds_write2_b32 v0, v14, v15 offset1:1
	v_add_u32_e32 v0, 0x1080, v32
	s_waitcnt vmcnt(3)
	ds_write2_b32 v0, v16, v17 offset1:1
	v_add_u32_e32 v0, 0x1088, v32
	ds_write2_b32 v0, v18, v19 offset1:1
	v_add_u32_e32 v0, 0x14a0, v32
	s_waitcnt vmcnt(2)
	ds_write2_b32 v0, v20, v21 offset1:1
	v_add_u32_e32 v0, 0x14a8, v32
	ds_write2_b32 v0, v22, v23 offset1:1
	v_add_u32_e32 v0, 0x18c0, v32
	s_waitcnt vmcnt(1)
	ds_write2_b32 v0, v24, v25 offset1:1
	v_add_u32_e32 v0, 0x18c8, v32
	ds_write2_b32 v0, v26, v27 offset1:1
	v_add_u32_e32 v0, 0x1ce0, v32
	s_waitcnt vmcnt(0)
	ds_write2_b32 v0, v28, v29 offset1:1
	v_add_u32_e32 v0, 0x1ce8, v32
	ds_write2_b32 v0, v30, v31 offset1:1
	s_waitcnt lgkmcnt(0)
	ds_read2_b32 v[6:7], v84 offset0:33 offset1:41
	ds_read2_b32 v[8:9], v84 offset1:8
	ds_read2_b32 v[10:11], v84 offset0:66 offset1:74
	ds_read2_b32 v[12:13], v84 offset0:99 offset1:107
	ds_read2_b32 v[14:15], v84 offset0:132 offset1:140
	ds_read2_b32 v[16:17], v84 offset0:165 offset1:173
	ds_read2_b32 v[18:19], v84 offset0:198 offset1:206
	ds_read2_b32 v[20:21], v84 offset0:231 offset1:239
	s_waitcnt lgkmcnt(7)
	v_bfe_u32 v3, v6, 16, 1
	s_waitcnt lgkmcnt(6)
	v_bfe_u32 v2, v8, 16, 1
	v_add3_u32 v2, v8, v2, s49
	v_lshrrev_b32_e32 v2, 16, v2
	v_add3_u32 v3, v6, v3, s49
	v_and_or_b32 v2, v3, s50, v2
	s_waitcnt lgkmcnt(5)
	v_bfe_u32 v3, v10, 16, 1
	v_add3_u32 v3, v10, v3, s49
	s_waitcnt lgkmcnt(4)
	v_bfe_u32 v4, v12, 16, 1
	v_lshrrev_b32_e32 v3, 16, v3
	v_add3_u32 v4, v12, v4, s49
	v_and_or_b32 v3, v4, s50, v3
	s_waitcnt lgkmcnt(3)
	v_bfe_u32 v4, v14, 16, 1
	v_add3_u32 v4, v14, v4, s49
	s_waitcnt lgkmcnt(2)
	v_bfe_u32 v5, v16, 16, 1
	v_lshrrev_b32_e32 v4, 16, v4
	v_add3_u32 v5, v16, v5, s49
	v_and_or_b32 v4, v5, s50, v4
	s_waitcnt lgkmcnt(1)
; #define LAS __attribute__((address_space(3)))
; __device__ __forceinline__ unsigned pk2(float lo, float hi) { return f2bf(lo) | (f2bf(hi) << 16); }
; #define LDS_WAIT() asm volatile("s_waitcnt lgkmcnt(0)" ::: "memory")
; template <class RM> __device__ __forceinline__ void tr_item(const float* __restrict__ W, int K, int N, bf16* __restrict__ WT, RM rm, const float* ks0, const float* ks1, int ksplit, LAS float* scr, int item, int lane) {
;     ...
;     for (int j = 0; j < 4; ++j) { const int n = (lane >> 3) + 8 * j; const LAS float* s = scr + (8 * c) * 33 + n;
;         v4u o; o.x = pk2(s[0 * 33], s[1 * 33]); o.y = pk2(s[2 * 33], s[3 * 33]); o.z = pk2(s[4 * 33], s[5 * 33]); o.w = pk2(s[6 * 33], s[7 * 33]);
;         *(v4u*)(WT + (size_t)rm(n0 + n) * K + k0 + 8 * c) = o; }
;     LDS_WAIT(); asm volatile("" ::: "memory");
	v_bfe_u32 v5, v18, 16, 1
	v_add3_u32 v5, v18, v5, s49
	s_waitcnt lgkmcnt(0)
	v_bfe_u32 v6, v20, 16, 1
	v_lshrrev_b32_e32 v5, 16, v5
	v_add3_u32 v6, v20, v6, s49
	v_and_or_b32 v5, v6, s50, v5
	v_or_b32_e32 v6, s0, v76
	v_mul_u32_u24_e32 v6, 0xb00, v6
	v_lshl_add_u64 v[0:1], v[64:65], 0, s[18:19]
	v_lshlrev_b32_e32 v36, 1, v6
	v_lshl_add_u64 v[22:23], v[0:1], 0, v[36:37]
	global_store_dwordx4 v[22:23], v[2:5], off
	v_bfe_u32 v6, v21, 16, 1
	v_add3_u32 v6, v21, v6, s49
	v_bfe_u32 v2, v9, 16, 1
	v_add3_u32 v2, v9, v2, s49
	v_bfe_u32 v3, v7, 16, 1
	v_lshrrev_b32_e32 v2, 16, v2
	v_add3_u32 v3, v7, v3, s49
	v_and_or_b32 v2, v3, s50, v2
	v_bfe_u32 v3, v11, 16, 1
	v_add3_u32 v3, v11, v3, s49
	v_bfe_u32 v4, v13, 16, 1
	v_lshrrev_b32_e32 v3, 16, v3
	v_add3_u32 v4, v13, v4, s49
	v_and_or_b32 v3, v4, s50, v3
	v_bfe_u32 v4, v15, 16, 1
	v_add3_u32 v4, v15, v4, s49
	v_bfe_u32 v5, v17, 16, 1
	v_lshrrev_b32_e32 v4, 16, v4
	v_add3_u32 v5, v17, v5, s49
	v_and_or_b32 v4, v5, s50, v4
	v_bfe_u32 v5, v19, 16, 1
	v_add3_u32 v5, v19, v5, s49
	v_lshrrev_b32_e32 v5, 16, v5
	v_and_or_b32 v5, v6, s50, v5
	v_or_b32_e32 v6, s0, v80
	v_mul_u32_u24_e32 v6, 0xb00, v6
	v_lshlrev_b32_e32 v36, 1, v6
	v_lshl_add_u64 v[6:7], v[0:1], 0, v[36:37]
	global_store_dwordx4 v[6:7], v[2:5], off
	ds_read2_b32 v[6:7], v84 offset0:16 offset1:24
	ds_read2_b32 v[8:9], v84 offset0:49 offset1:57
	ds_read2_b32 v[10:11], v84 offset0:82 offset1:90
	ds_read2_b32 v[12:13], v84 offset0:115 offset1:123
	ds_read2_b32 v[14:15], v84 offset0:148 offset1:156
	ds_read2_b32 v[16:17], v84 offset0:181 offset1:189
	ds_read2_b32 v[18:19], v84 offset0:214 offset1:222
	ds_read2_b32 v[20:21], v84 offset0:247 offset1:255
	s_waitcnt lgkmcnt(7)
	v_bfe_u32 v2, v6, 16, 1
	v_add3_u32 v2, v6, v2, s49
	s_waitcnt lgkmcnt(6)
	v_bfe_u32 v3, v8, 16, 1
	v_lshrrev_b32_e32 v2, 16, v2
	v_add3_u32 v3, v8, v3, s49
	v_and_or_b32 v2, v3, s50, v2
	s_waitcnt lgkmcnt(5)
	v_bfe_u32 v3, v10, 16, 1
	v_add3_u32 v3, v10, v3, s49
	s_waitcnt lgkmcnt(4)
	v_bfe_u32 v4, v12, 16, 1
	v_lshrrev_b32_e32 v3, 16, v3
	v_add3_u32 v4, v12, v4, s49
	v_and_or_b32 v3, v4, s50, v3
	s_waitcnt lgkmcnt(3)
	v_bfe_u32 v4, v14, 16, 1
	v_add3_u32 v4, v14, v4, s49
	s_waitcnt lgkmcnt(2)
	v_bfe_u32 v5, v16, 16, 1
	v_lshrrev_b32_e32 v4, 16, v4
	v_add3_u32 v5, v16, v5, s49
	v_and_or_b32 v4, v5, s50, v4
	s_waitcnt lgkmcnt(1)
	v_bfe_u32 v5, v18, 16, 1
	v_add3_u32 v5, v18, v5, s49
	s_waitcnt lgkmcnt(0)
	v_bfe_u32 v6, v20, 16, 1
	v_lshrrev_b32_e32 v5, 16, v5
	v_add3_u32 v6, v20, v6, s49
	v_and_or_b32 v5, v6, s50, v5
	v_or_b32_e32 v6, s0, v81
	v_mul_u32_u24_e32 v6, 0xb00, v6
	v_lshlrev_b32_e32 v36, 1, v6
	v_lshl_add_u64 v[22:23], v[0:1], 0, v[36:37]
	global_store_dwordx4 v[22:23], v[2:5], off
	v_bfe_u32 v6, v21, 16, 1
	v_add3_u32 v6, v21, v6, s49
	v_bfe_u32 v2, v7, 16, 1
	v_add3_u32 v2, v7, v2, s49
	v_bfe_u32 v3, v9, 16, 1
	v_lshrrev_b32_e32 v2, 16, v2
	v_add3_u32 v3, v9, v3, s49
	v_and_or_b32 v2, v3, s50, v2
	v_bfe_u32 v3, v11, 16, 1
	v_add3_u32 v3, v11, v3, s49
	v_bfe_u32 v4, v13, 16, 1
	v_lshrrev_b32_e32 v3, 16, v3
	v_add3_u32 v4, v13, v4, s49
	v_and_or_b32 v3, v4, s50, v3
	v_bfe_u32 v4, v15, 16, 1
	v_add3_u32 v4, v15, v4, s49
	v_bfe_u32 v5, v17, 16, 1
	v_lshrrev_b32_e32 v4, 16, v4
	v_add3_u32 v5, v17, v5, s49
	v_and_or_b32 v4, v5, s50, v4
	v_bfe_u32 v5, v19, 16, 1
	v_add3_u32 v5, v19, v5, s49
	v_lshrrev_b32_e32 v5, 16, v5
	v_and_or_b32 v5, v6, s50, v5
	v_or_b32_e32 v6, s0, v83
	v_mul_u32_u24_e32 v6, 0xb00, v6
	v_lshlrev_b32_e32 v36, 1, v6
	v_lshl_add_u64 v[0:1], v[0:1], 0, v[36:37]
	global_store_dwordx4 v[0:1], v[2:5], off
	s_waitcnt lgkmcnt(0)

; #define LAS __attribute__((address_space(3)))
; __device__ __forceinline__ unsigned pk2(float lo, float hi) { return f2bf(lo) | (f2bf(hi) << 16); }
; #define LDS_WAIT() asm volatile("s_waitcnt lgkmcnt(0)" ::: "memory")
; template <class RM> __device__ __forceinline__ void tr_item(const float* __restrict__ W, int K, int N, bf16* __restrict__ WT, RM rm, const float* ks0, const float* ks1, int ksplit, LAS float* scr, int item, int lane) {
;     ...
;     for (int i = 0; i < 8; ++i) wv[i] = *(const f32x4*)(W + (size_t)(k0 + 8 * i + r8) * N + n0 + 4 * cg);
;     const f32x4 cs = {rm.scale(n0 + 4 * cg), rm.scale(n0 + 4 * cg + 1), rm.scale(n0 + 4 * cg + 2), rm.scale(n0 + 4 * cg + 3)};
; #pragma unroll
;     for (int i = 0; i < 8; ++i) { const int kk = 8 * i + r8; f32x4 w = wv[i] * cs;
;         if (ks0) { const int k = k0 + kk; w = w * ((k < ksplit) ? ks0[k] : ks1[k - ksplit]); }
;         scr[kk * 33 + 4 * cg] = w[0]; scr[kk * 33 + 4 * cg + 1] = w[1]; scr[kk * 33 + 4 * cg + 2] = w[2]; scr[kk * 33 + 4 * cg + 3] = w[3]; }
;     LDS_WAIT(); asm volatile("" ::: "memory");
;     const int c = lane & 7;
; #pragma unroll
;     for (int j = 0; j < 4; ++j) { const int n = (lane >> 3) + 8 * j; const LAS float* s = scr + (8 * c) * 33 + n;
;         v4u o; o.x = pk2(s[0 * 33], s[1 * 33]); o.y = pk2(s[2 * 33], s[3 * 33]); o.z = pk2(s[4 * 33], s[5 * 33]); o.w = pk2(s[6 * 33], s[7 * 33]);
.LBB0_199:
	s_andn2_b64 vcc, exec, s[0:1]
	s_cbranch_vccnz .LBB0_55
	s_mul_hi_i32 s0, s3, 0x2e8ba2e9
	s_lshr_b32 s1, s0, 31
	s_ashr_i32 s0, s0, 5
	s_add_i32 s0, s0, s1
	s_lshl_b32 s64, s0, 6
	s_mulk_i32 s0, 0xea00
	s_add_i32 s0, s9, s0
	v_or_b32_e32 v32, s64, v76
	s_ashr_i32 s1, s0, 31
	v_lshl_add_u64 v[0:1], s[0:1], 2, v[66:67]
	v_or_b32_e32 v4, 8, v32
	v_mad_i64_i32 v[2:3], s[58:59], v32, s68, v[0:1]
	v_mad_i64_i32 v[8:9], s[58:59], v4, s68, v[0:1]
	global_load_dwordx4 v[4:7], v[2:3], off nt
	s_nop 0
	global_load_dwordx4 v[8:11], v[8:9], off nt
	v_or_b32_e32 v2, 16, v32
	v_or_b32_e32 v12, 24, v32
	v_mad_i64_i32 v[2:3], s[58:59], v2, s68, v[0:1]
	v_mad_i64_i32 v[16:17], s[58:59], v12, s68, v[0:1]
	global_load_dwordx4 v[12:15], v[2:3], off nt
	s_nop 0
	global_load_dwordx4 v[16:19], v[16:17], off nt
	v_or_b32_e32 v2, 32, v32
	v_or_b32_e32 v20, 40, v32
	v_mad_i64_i32 v[2:3], s[58:59], v2, s68, v[0:1]
	v_mad_i64_i32 v[24:25], s[58:59], v20, s68, v[0:1]
	global_load_dwordx4 v[20:23], v[2:3], off nt
	s_nop 0
	global_load_dwordx4 v[24:27], v[24:25], off nt
	v_or_b32_e32 v2, 48, v32
	v_mad_i64_i32 v[2:3], s[58:59], v2, s68, v[0:1]
	global_load_dwordx4 v[28:31], v[2:3], off nt
	v_or_b32_e32 v2, 56, v32
	v_mad_i64_i32 v[0:1], s[58:59], v2, s68, v[0:1]
	global_load_dwordx4 v[0:3], v[0:1], off nt
	v_add_u32_e32 v34, s0, v77
	v_cmp_lt_i32_e32 vcc, s47, v34
	v_add_u32_e32 v35, 2, v34
	v_add_u32_e32 v104, 3, v34
	v_cndmask_b32_e32 v32, v96, v97, vcc
	v_cmp_lt_i32_e32 vcc, s69, v34
	v_add_u32_e32 v36, v78, v79
	v_add_u32_e32 v70, 0x420, v36
	v_cndmask_b32_e32 v33, v96, v97, vcc
	v_cmp_lt_i32_e32 vcc, s47, v35
	v_add_u32_e32 v71, 0x428, v36
	v_add_u32_e32 v72, 0x840, v36
	v_cndmask_b32_e32 v34, v96, v97, vcc
	v_cmp_lt_i32_e32 vcc, s47, v104
	v_add_u32_e32 v73, 0x848, v36
	v_add_u32_e32 v74, 0xc60, v36
	v_cndmask_b32_e32 v35, v96, v97, vcc
	v_add_u32_e32 v75, 0xc68, v36
	v_add_u32_e32 v99, 0x1080, v36
	v_add_u32_e32 v100, 0x1088, v36
	v_add_u32_e32 v101, 0x14a0, v36
	v_add_u32_e32 v102, 0x14a8, v36
	v_add_u32_e32 v103, 0x18c0, v36
	s_ashr_i32 s65, s64, 31
	s_waitcnt vmcnt(7)
	v_pk_mul_f32 v[4:5], v[32:33], v[4:5]
	v_pk_mul_f32 v[6:7], v[34:35], v[6:7]
	s_waitcnt vmcnt(6)
	v_pk_mul_f32 v[10:11], v[34:35], v[10:11]
	v_pk_mul_f32 v[8:9], v[32:33], v[8:9]
	s_waitcnt vmcnt(5)
	v_pk_mul_f32 v[14:15], v[34:35], v[14:15]
	v_pk_mul_f32 v[12:13], v[32:33], v[12:13]
	s_waitcnt vmcnt(4)
	v_pk_mul_f32 v[18:19], v[34:35], v[18:19]
	v_pk_mul_f32 v[16:17], v[32:33], v[16:17]
	s_waitcnt vmcnt(3)
	v_pk_mul_f32 v[22:23], v[34:35], v[22:23]
	v_pk_mul_f32 v[20:21], v[32:33], v[20:21]
	s_waitcnt vmcnt(2)
	v_pk_mul_f32 v[26:27], v[34:35], v[26:27]
	v_pk_mul_f32 v[24:25], v[32:33], v[24:25]
	s_waitcnt vmcnt(1)
	v_pk_mul_f32 v[30:31], v[34:35], v[30:31]
	v_pk_mul_f32 v[28:29], v[32:33], v[28:29]
	ds_write2_b32 v36, v4, v5 offset1:1
	ds_write2_b32 v36, v6, v7 offset0:2 offset1:3
	ds_write2_b32 v70, v8, v9 offset1:1
	ds_write2_b32 v71, v10, v11 offset1:1
	ds_write2_b32 v72, v12, v13 offset1:1
	ds_write2_b32 v73, v14, v15 offset1:1
	ds_write2_b32 v74, v16, v17 offset1:1
	ds_write2_b32 v75, v18, v19 offset1:1
	ds_write2_b32 v99, v20, v21 offset1:1
	ds_write2_b32 v100, v22, v23 offset1:1
	ds_write2_b32 v101, v24, v25 offset1:1
	ds_write2_b32 v102, v26, v27 offset1:1
	ds_write2_b32 v103, v28, v29 offset1:1
	v_add_u32_e32 v4, 0x18c8, v36
	ds_write2_b32 v4, v30, v31 offset1:1
	s_waitcnt vmcnt(0)
	v_pk_mul_f32 v[0:1], v[32:33], v[0:1]
	v_add_u32_e32 v4, 0x1ce0, v36
	v_pk_mul_f32 v[2:3], v[34:35], v[2:3]
	ds_write2_b32 v4, v0, v1 offset1:1
	v_add_u32_e32 v0, 0x1ce8, v36
	ds_write2_b32 v0, v2, v3 offset1:1
	s_waitcnt lgkmcnt(0)
	ds_read2_b32 v[6:7], v84 offset1:8
	ds_read2_b32 v[8:9], v84 offset0:33 offset1:41
	ds_read2_b32 v[10:11], v84 offset0:66 offset1:74
	ds_read2_b32 v[12:13], v84 offset0:99 offset1:107
	ds_read2_b32 v[14:15], v84 offset0:132 offset1:140
	s_waitcnt lgkmcnt(4)
	v_bfe_u32 v2, v6, 16, 1
	v_add3_u32 v2, v6, v2, s49
	s_waitcnt lgkmcnt(3)
	v_bfe_u32 v3, v8, 16, 1
	v_lshrrev_b32_e32 v2, 16, v2
	v_add3_u32 v3, v8, v3, s49
	ds_read2_b32 v[16:17], v84 offset0:165 offset1:173
	v_and_or_b32 v2, v3, s50, v2
	s_waitcnt lgkmcnt(3)
	v_bfe_u32 v3, v10, 16, 1
	v_add3_u32 v3, v10, v3, s49
	s_waitcnt lgkmcnt(2)
	v_bfe_u32 v4, v12, 16, 1
	ds_read2_b32 v[18:19], v84 offset0:198 offset1:206
	v_lshrrev_b32_e32 v3, 16, v3
	v_add3_u32 v4, v12, v4, s49
	ds_read2_b32 v[20:21], v84 offset0:231 offset1:239
	v_and_or_b32 v3, v4, s50, v3
	s_waitcnt lgkmcnt(3)
	v_bfe_u32 v4, v14, 16, 1
	v_add3_u32 v4, v14, v4, s49
	s_waitcnt lgkmcnt(2)
	v_bfe_u32 v5, v16, 16, 1
	v_lshrrev_b32_e32 v4, 16, v4
	v_add3_u32 v5, v16, v5, s49
	v_and_or_b32 v4, v5, s50, v4
	s_waitcnt lgkmcnt(1)
; #define LAS __attribute__((address_space(3)))
; __device__ __forceinline__ unsigned pk2(float lo, float hi) { return f2bf(lo) | (f2bf(hi) << 16); }
; template <class RM> __device__ __forceinline__ void tr_item(const float* __restrict__ W, int K, int N, bf16* __restrict__ WT, RM rm, const float* ks0, const float* ks1, int ksplit, LAS float* scr, int item, int lane) {
;     ...
;     const int c = lane & 7;
; #pragma unroll
;     for (int j = 0; j < 4; ++j) { const int n = (lane >> 3) + 8 * j; const LAS float* s = scr + (8 * c) * 33 + n;
;         v4u o; o.x = pk2(s[0 * 33], s[1 * 33]); o.y = pk2(s[2 * 33], s[3 * 33]); o.z = pk2(s[4 * 33], s[5 * 33]); o.w = pk2(s[6 * 33], s[7 * 33]);
;         *(v4u*)(WT + (size_t)rm(n0 + n) * K + k0 + 8 * c) = o; }
	v_bfe_u32 v5, v18, 16, 1
	v_add3_u32 v5, v18, v5, s49
	s_waitcnt lgkmcnt(0)
	v_bfe_u32 v6, v20, 16, 1
	v_lshrrev_b32_e32 v5, 16, v5
	v_add3_u32 v6, v20, v6, s49
	v_add_u32_e32 v24, s0, v76
	v_and_or_b32 v5, v6, s50, v5
	v_add_u32_e32 v6, 0xfffff500, v24
	v_cmp_lt_i32_e32 vcc, s47, v24
	v_lshl_add_u64 v[0:1], s[64:65], 1, v[68:69]
	s_nop 0
	v_cndmask_b32_e32 v6, v24, v6, vcc
	v_lshlrev_b32_e32 v8, 1, v6
	v_and_b32_e32 v8, 0xffffff00, v8
	v_cndmask_b32_e32 v10, 0, v98, vcc
	v_and_b32_e32 v6, 0x67, v6
	v_or3_b32 v22, v6, v10, v8
	v_ashrrev_i32_e32 v23, 31, v22
	v_lshlrev_b64 v[22:23], 11, v[22:23]
	v_lshl_add_u64 v[22:23], v[0:1], 0, v[22:23]
	global_store_dwordx4 v[22:23], v[2:5], off
	v_bfe_u32 v6, v21, 16, 1
	v_add3_u32 v6, v21, v6, s49
	v_bfe_u32 v2, v7, 16, 1
	v_add3_u32 v2, v7, v2, s49
	v_bfe_u32 v3, v9, 16, 1
	v_lshrrev_b32_e32 v2, 16, v2
	v_add3_u32 v3, v9, v3, s49
	v_and_or_b32 v2, v3, s50, v2
	v_bfe_u32 v3, v11, 16, 1
	v_add3_u32 v3, v11, v3, s49
	v_bfe_u32 v4, v13, 16, 1
	v_lshrrev_b32_e32 v3, 16, v3
	v_add3_u32 v4, v13, v4, s49
	v_and_or_b32 v3, v4, s50, v3
	v_bfe_u32 v4, v15, 16, 1
	v_add3_u32 v4, v15, v4, s49
	v_bfe_u32 v5, v17, 16, 1
	v_lshrrev_b32_e32 v4, 16, v4
	v_add3_u32 v5, v17, v5, s49
	v_and_or_b32 v4, v5, s50, v4
	v_bfe_u32 v5, v19, 16, 1
	v_add3_u32 v5, v19, v5, s49
	v_lshrrev_b32_e32 v5, 16, v5
	v_and_or_b32 v5, v6, s50, v5
	v_add_u32_e32 v6, 8, v24
	v_add_u32_e32 v7, 0xfffff508, v24
	v_cmp_lt_i32_e32 vcc, s47, v6
	ds_read2_b32 v[10:11], v84 offset0:82 offset1:90
	ds_read2_b32 v[12:13], v84 offset0:115 offset1:123
	v_cndmask_b32_e32 v6, v6, v7, vcc
	v_lshlrev_b32_e32 v7, 1, v6
	v_and_b32_e32 v7, 0xffffff00, v7
	v_cndmask_b32_e32 v8, 0, v98, vcc
	v_and_b32_e32 v6, 0x6f, v6
	v_or3_b32 v6, v6, v8, v7
	v_ashrrev_i32_e32 v7, 31, v6
	v_lshlrev_b64 v[6:7], 11, v[6:7]
	ds_read2_b32 v[8:9], v84 offset0:16 offset1:24
	v_lshl_add_u64 v[6:7], v[0:1], 0, v[6:7]
	global_store_dwordx4 v[6:7], v[2:5], off
	ds_read2_b32 v[6:7], v84 offset0:49 offset1:57
	ds_read2_b32 v[14:15], v84 offset0:148 offset1:156
	s_waitcnt lgkmcnt(2)
	v_bfe_u32 v2, v8, 16, 1
	v_add3_u32 v2, v8, v2, s49
	v_lshrrev_b32_e32 v2, 16, v2
	s_waitcnt lgkmcnt(1)
	v_bfe_u32 v3, v6, 16, 1
	v_add3_u32 v3, v6, v3, s49
	ds_read2_b32 v[16:17], v84 offset0:181 offset1:189
	v_and_or_b32 v2, v3, s50, v2
	v_bfe_u32 v3, v10, 16, 1
	v_add3_u32 v3, v10, v3, s49
	v_bfe_u32 v4, v12, 16, 1
	ds_read2_b32 v[18:19], v84 offset0:214 offset1:222
	v_lshrrev_b32_e32 v3, 16, v3
	v_add3_u32 v4, v12, v4, s49
	ds_read2_b32 v[20:21], v84 offset0:247 offset1:255
	v_and_or_b32 v3, v4, s50, v3
	s_waitcnt lgkmcnt(3)
	v_bfe_u32 v4, v14, 16, 1
	v_add3_u32 v4, v14, v4, s49
	s_waitcnt lgkmcnt(2)
	v_bfe_u32 v5, v16, 16, 1
	v_lshrrev_b32_e32 v4, 16, v4
	v_add3_u32 v5, v16, v5, s49
	v_and_or_b32 v4, v5, s50, v4
	s_waitcnt lgkmcnt(1)
	v_bfe_u32 v5, v18, 16, 1
	v_add3_u32 v5, v18, v5, s49
	s_waitcnt lgkmcnt(0)
	v_bfe_u32 v6, v20, 16, 1
	v_lshrrev_b32_e32 v5, 16, v5
	v_add3_u32 v6, v20, v6, s49
	v_and_or_b32 v5, v6, s50, v5
	v_add_u32_e32 v6, 16, v24
	v_add_u32_e32 v8, 0xfffff510, v24
	v_cmp_lt_i32_e32 vcc, s47, v6
	s_nop 1
	v_cndmask_b32_e32 v6, v6, v8, vcc
	v_lshlrev_b32_e32 v8, 1, v6
	v_and_b32_e32 v8, 0xffffff00, v8
	v_cndmask_b32_e32 v10, 0, v98, vcc
	v_and_b32_e32 v6, 0x77, v6
	v_or3_b32 v22, v6, v10, v8
	v_ashrrev_i32_e32 v23, 31, v22
	v_lshlrev_b64 v[22:23], 11, v[22:23]
	v_lshl_add_u64 v[22:23], v[0:1], 0, v[22:23]
	global_store_dwordx4 v[22:23], v[2:5], off
	v_bfe_u32 v6, v21, 16, 1
	v_add3_u32 v6, v21, v6, s49
	v_bfe_u32 v2, v9, 16, 1
	v_add3_u32 v2, v9, v2, s49
	v_bfe_u32 v3, v7, 16, 1
	v_lshrrev_b32_e32 v2, 16, v2
	v_add3_u32 v3, v7, v3, s49
	v_and_or_b32 v2, v3, s50, v2
	v_bfe_u32 v3, v11, 16, 1
	v_add3_u32 v3, v11, v3, s49
	v_bfe_u32 v4, v13, 16, 1
	v_lshrrev_b32_e32 v3, 16, v3
	v_add3_u32 v4, v13, v4, s49
	v_and_or_b32 v3, v4, s50, v3
	v_bfe_u32 v4, v15, 16, 1
	v_add3_u32 v4, v15, v4, s49
	v_bfe_u32 v5, v17, 16, 1
	v_lshrrev_b32_e32 v4, 16, v4
	v_add3_u32 v5, v17, v5, s49
	v_and_or_b32 v4, v5, s50, v4
	v_bfe_u32 v5, v19, 16, 1
	v_add3_u32 v5, v19, v5, s49
	v_lshrrev_b32_e32 v5, 16, v5
	v_and_or_b32 v5, v6, s50, v5
	v_add_u32_e32 v6, 24, v24
	v_add_u32_e32 v7, 0xfffff518, v24
	v_cmp_lt_i32_e32 vcc, s47, v6
	s_nop 1
	v_cndmask_b32_e32 v6, v6, v7, vcc
	v_lshlrev_b32_e32 v7, 1, v6
	v_and_b32_e32 v7, 0xffffff00, v7
	v_cndmask_b32_e32 v8, 0, v98, vcc
	v_and_b32_e32 v6, 0x7f, v6
	v_or3_b32 v6, v6, v8, v7
	v_ashrrev_i32_e32 v7, 31, v6
	v_lshlrev_b64 v[6:7], 11, v[6:7]
	v_lshl_add_u64 v[0:1], v[0:1], 0, v[6:7]
	global_store_dwordx4 v[0:1], v[2:5], off
	s_waitcnt lgkmcnt(0)
	s_branch .LBB0_55

; __device__ __forceinline__ unsigned cvt_pk_bf16(float lo, float hi) { f32x2c_t v = {lo, hi}; bf16x2c_t b = __builtin_convertvector(v, bf16x2c_t); return __builtin_bit_cast(unsigned, b); }
; __device__ __forceinline__ unsigned swi2(float a0, float a1, float b0, float b1) {
;     const f32x2s a = {a0, a1}, b = {b0, b1};
;     f32x2s e; e.x = __builtin_amdgcn_exp2f(-a.x); e.y = __builtin_amdgcn_exp2f(-a.y);
;     const f32x2s d = e + 1.0f; f32x2s r; r.x = __builtin_amdgcn_rcpf(d.x); r.y = __builtin_amdgcn_rcpf(d.y);
;     const f32x2s o = (a * b) * r;
;     return cvt_pk_bf16(o.x, o.y);
; }
;     __device__ __forceinline__ void operator()(const f32x4 (&acc)[2][2][4][2], const Unit& u, int wr, int wc, int fr, int fq) const {
;     ...
;         for (int ai = 0; ai < 2; ++ai)
; #pragma unroll
;             for (int m = 0; m < 4; ++m) {
;                 bf16_t* rowp = O + (size_t)(row0 + ai * HALF + m * 16) * 2816 + col0;
;                 const f32x4 a0 = acc[ai][0][m][0], a1 = acc[ai][0][m][1], b0 = acc[ai][1][m][0], b1 = acc[ai][1][m][1];
;                 u32x4 w;
;                 w.x = swi2(a0[0], a0[1], b0[0], b0[1]); w.y = swi2(a0[2], a0[3], b0[2], b0[3]);
;                 w.z = swi2(a1[0], a1[1], b1[0], b1[1]); w.w = swi2(a1[2], a1[3], b1[2], b1[3]);
.LBB0_279:
	v_exp_f32_e64 v158, -v126
	v_exp_f32_e64 v159, -v127
	v_exp_f32_e64 v154, -v124
	v_exp_f32_e64 v155, -v125
	v_pk_mul_f32 v[120:121], v[124:125], v[120:121]
	v_pk_add_f32 v[124:125], v[158:159], 1.0 op_sel_hi:[1,0]
	v_pk_mul_f32 v[122:123], v[126:127], v[122:123]
	v_rcp_f32_e32 v124, v124
	v_rcp_f32_e32 v125, v125
	v_pk_add_f32 v[154:155], v[154:155], 1.0 op_sel_hi:[1,0]
	v_exp_f32_e64 v126, -v116
	v_rcp_f32_e32 v154, v154
	v_rcp_f32_e32 v155, v155
	v_exp_f32_e64 v127, -v117
	v_pk_mul_f32 v[122:123], v[124:125], v[122:123]
	v_exp_f32_e64 v124, -v118
	v_exp_f32_e64 v125, -v119
	v_pk_mul_f32 v[120:121], v[154:155], v[120:121]
	v_pk_mul_f32 v[114:115], v[118:119], v[114:115]
	v_cvt_pk_bf16_f32 v120, v120, v121
	v_cvt_pk_bf16_f32 v121, v122, v123
	v_pk_add_f32 v[122:123], v[126:127], 1.0 op_sel_hi:[1,0]
	v_pk_add_f32 v[118:119], v[124:125], 1.0 op_sel_hi:[1,0]
	v_rcp_f32_e32 v122, v122
	v_rcp_f32_e32 v123, v123
	v_rcp_f32_e32 v118, v118
	v_rcp_f32_e32 v119, v119
	v_pk_mul_f32 v[112:113], v[116:117], v[112:113]
	v_exp_f32_e64 v116, -v110
	v_pk_mul_f32 v[112:113], v[122:123], v[112:113]
	v_exp_f32_e64 v117, -v111
	v_cvt_pk_bf16_f32 v122, v112, v113
	v_pk_mul_f32 v[112:113], v[118:119], v[114:115]
	v_pk_mul_f32 v[104:105], v[108:109], v[104:105]
	v_cvt_pk_bf16_f32 v123, v112, v113
	v_exp_f32_e64 v112, -v108
	v_exp_f32_e64 v113, -v109
	v_pk_add_f32 v[108:109], v[116:117], 1.0 op_sel_hi:[1,0]
	v_pk_mul_f32 v[106:107], v[110:111], v[106:107]
	v_rcp_f32_e32 v108, v108
	v_rcp_f32_e32 v109, v109
	v_pk_add_f32 v[112:113], v[112:113], 1.0 op_sel_hi:[1,0]
	v_exp_f32_e64 v110, -v100
	v_rcp_f32_e32 v112, v112
	v_rcp_f32_e32 v113, v113
	v_exp_f32_e64 v111, -v101
	v_pk_mul_f32 v[106:107], v[108:109], v[106:107]
	v_exp_f32_e64 v108, -v102
	v_exp_f32_e64 v109, -v103
	v_pk_mul_f32 v[104:105], v[112:113], v[104:105]
	v_pk_mul_f32 v[98:99], v[102:103], v[98:99]
	v_cvt_pk_bf16_f32 v104, v104, v105
	v_cvt_pk_bf16_f32 v105, v106, v107
	v_pk_add_f32 v[106:107], v[110:111], 1.0 op_sel_hi:[1,0]
	v_pk_add_f32 v[102:103], v[108:109], 1.0 op_sel_hi:[1,0]
	v_rcp_f32_e32 v106, v106
	v_rcp_f32_e32 v107, v107
	v_rcp_f32_e32 v102, v102
	v_rcp_f32_e32 v103, v103
	v_pk_mul_f32 v[96:97], v[100:101], v[96:97]
	v_exp_f32_e64 v100, -v94
	v_pk_mul_f32 v[96:97], v[106:107], v[96:97]
	v_exp_f32_e64 v101, -v95
	v_cvt_pk_bf16_f32 v106, v96, v97
	v_pk_mul_f32 v[96:97], v[102:103], v[98:99]
	v_pk_mul_f32 v[88:89], v[92:93], v[88:89]
	v_cvt_pk_bf16_f32 v107, v96, v97
	v_exp_f32_e64 v96, -v92
	v_exp_f32_e64 v97, -v93
	v_pk_add_f32 v[92:93], v[100:101], 1.0 op_sel_hi:[1,0]
	v_pk_mul_f32 v[90:91], v[94:95], v[90:91]
	v_rcp_f32_e32 v92, v92
	v_rcp_f32_e32 v93, v93
	v_pk_add_f32 v[96:97], v[96:97], 1.0 op_sel_hi:[1,0]
	v_exp_f32_e64 v94, -v84
	v_rcp_f32_e32 v96, v96
	v_rcp_f32_e32 v97, v97
	v_exp_f32_e64 v95, -v85
	v_pk_mul_f32 v[90:91], v[92:93], v[90:91]
	v_exp_f32_e64 v92, -v86
	v_exp_f32_e64 v93, -v87
	v_pk_mul_f32 v[88:89], v[96:97], v[88:89]
	v_pk_mul_f32 v[82:83], v[86:87], v[82:83]
	v_cvt_pk_bf16_f32 v88, v88, v89
	v_cvt_pk_bf16_f32 v89, v90, v91
	v_pk_add_f32 v[90:91], v[94:95], 1.0 op_sel_hi:[1,0]
	v_pk_add_f32 v[86:87], v[92:93], 1.0 op_sel_hi:[1,0]
	v_rcp_f32_e32 v90, v90
	v_rcp_f32_e32 v91, v91
	v_rcp_f32_e32 v86, v86
	v_rcp_f32_e32 v87, v87
	v_pk_mul_f32 v[80:81], v[84:85], v[80:81]
	v_exp_f32_e64 v84, -v78
	v_pk_mul_f32 v[80:81], v[90:91], v[80:81]
	v_exp_f32_e64 v85, -v79
	v_cvt_pk_bf16_f32 v90, v80, v81
	v_pk_mul_f32 v[80:81], v[86:87], v[82:83]
	v_pk_mul_f32 v[72:73], v[76:77], v[72:73]
	v_cvt_pk_bf16_f32 v91, v80, v81
	v_exp_f32_e64 v80, -v76
	v_exp_f32_e64 v81, -v77
	v_pk_add_f32 v[76:77], v[84:85], 1.0 op_sel_hi:[1,0]
	v_pk_mul_f32 v[74:75], v[78:79], v[74:75]
	v_rcp_f32_e32 v76, v76
	v_rcp_f32_e32 v77, v77
	v_pk_add_f32 v[80:81], v[80:81], 1.0 op_sel_hi:[1,0]
	v_exp_f32_e64 v78, -v68
	v_rcp_f32_e32 v80, v80
	v_rcp_f32_e32 v81, v81
	v_exp_f32_e64 v79, -v69
	v_pk_mul_f32 v[74:75], v[76:77], v[74:75]
	v_exp_f32_e64 v76, -v70
	v_exp_f32_e64 v77, -v71
	v_pk_mul_f32 v[72:73], v[80:81], v[72:73]
	v_pk_mul_f32 v[66:67], v[70:71], v[66:67]
	v_cvt_pk_bf16_f32 v72, v72, v73
	v_cvt_pk_bf16_f32 v73, v74, v75
	v_pk_add_f32 v[74:75], v[78:79], 1.0 op_sel_hi:[1,0]
	v_pk_add_f32 v[70:71], v[76:77], 1.0 op_sel_hi:[1,0]
	v_rcp_f32_e32 v74, v74
	v_rcp_f32_e32 v75, v75
	v_rcp_f32_e32 v70, v70
	v_rcp_f32_e32 v71, v71
	v_pk_mul_f32 v[64:65], v[68:69], v[64:65]
	v_exp_f32_e64 v68, -v62
	v_pk_mul_f32 v[64:65], v[74:75], v[64:65]
	v_exp_f32_e64 v69, -v63
	v_cvt_pk_bf16_f32 v74, v64, v65
	v_pk_mul_f32 v[64:65], v[70:71], v[66:67]
	v_pk_mul_f32 v[56:57], v[60:61], v[56:57]
	v_cvt_pk_bf16_f32 v75, v64, v65
	v_exp_f32_e64 v64, -v60
	v_exp_f32_e64 v65, -v61
	v_pk_add_f32 v[60:61], v[68:69], 1.0 op_sel_hi:[1,0]
	v_pk_mul_f32 v[58:59], v[62:63], v[58:59]
	v_rcp_f32_e32 v60, v60
	v_rcp_f32_e32 v61, v61
	v_pk_add_f32 v[64:65], v[64:65], 1.0 op_sel_hi:[1,0]
	v_exp_f32_e64 v62, -v52
	v_rcp_f32_e32 v64, v64
	v_rcp_f32_e32 v65, v65
	v_exp_f32_e64 v63, -v53
	v_pk_mul_f32 v[58:59], v[60:61], v[58:59]
	v_exp_f32_e64 v60, -v54
	v_exp_f32_e64 v61, -v55
	v_pk_mul_f32 v[56:57], v[64:65], v[56:57]
	v_pk_mul_f32 v[50:51], v[54:55], v[50:51]
	v_cvt_pk_bf16_f32 v56, v56, v57
; __device__ __forceinline__ unsigned cvt_pk_bf16(float lo, float hi) { f32x2c_t v = {lo, hi}; bf16x2c_t b = __builtin_convertvector(v, bf16x2c_t); return __builtin_bit_cast(unsigned, b); }
; __device__ __forceinline__ unsigned swi2(float a0, float a1, float b0, float b1) {
;     const f32x2s a = {a0, a1}, b = {b0, b1};
;     f32x2s e; e.x = __builtin_amdgcn_exp2f(-a.x); e.y = __builtin_amdgcn_exp2f(-a.y);
;     const f32x2s d = e + 1.0f; f32x2s r; r.x = __builtin_amdgcn_rcpf(d.x); r.y = __builtin_amdgcn_rcpf(d.y);
;     const f32x2s o = (a * b) * r;
;     return cvt_pk_bf16(o.x, o.y);
;     __device__ __forceinline__ void operator()(const f32x4 (&acc)[2][2][4][2], const Unit& u, int wr, int wc, int fr, int fq) const {
;     ...
;         const int row0 = u.pm * BM + wr * 64 + fr, col0 = u.pn * 128 + wc * 32 + 8 * fq;
; #pragma unroll
;         for (int ai = 0; ai < 2; ++ai)
; #pragma unroll
;             for (int m = 0; m < 4; ++m) {
;                 bf16_t* rowp = O + (size_t)(row0 + ai * HALF + m * 16) * 2816 + col0;
;                 const f32x4 a0 = acc[ai][0][m][0], a1 = acc[ai][0][m][1], b0 = acc[ai][1][m][0], b1 = acc[ai][1][m][1];
;                 u32x4 w;
;                 w.x = swi2(a0[0], a0[1], b0[0], b0[1]); w.y = swi2(a0[2], a0[3], b0[2], b0[3]);
;                 w.z = swi2(a1[0], a1[1], b1[0], b1[1]); w.w = swi2(a1[2], a1[3], b1[2], b1[3]);
;                 *(u32x4*)rowp = w;
	v_cvt_pk_bf16_f32 v57, v58, v59
	v_pk_add_f32 v[58:59], v[62:63], 1.0 op_sel_hi:[1,0]
	v_pk_add_f32 v[54:55], v[60:61], 1.0 op_sel_hi:[1,0]
	v_rcp_f32_e32 v58, v58
	v_rcp_f32_e32 v59, v59
	v_rcp_f32_e32 v54, v54
	v_rcp_f32_e32 v55, v55
	v_pk_mul_f32 v[48:49], v[52:53], v[48:49]
	v_exp_f32_e64 v52, -v46
	v_pk_mul_f32 v[48:49], v[58:59], v[48:49]
	v_exp_f32_e64 v53, -v47
	v_cvt_pk_bf16_f32 v58, v48, v49
	v_pk_mul_f32 v[48:49], v[54:55], v[50:51]
	v_pk_mul_f32 v[40:41], v[44:45], v[40:41]
	v_cvt_pk_bf16_f32 v59, v48, v49
	v_exp_f32_e64 v48, -v44
	v_exp_f32_e64 v49, -v45
	v_pk_add_f32 v[44:45], v[52:53], 1.0 op_sel_hi:[1,0]
	v_pk_mul_f32 v[42:43], v[46:47], v[42:43]
	v_rcp_f32_e32 v44, v44
	v_rcp_f32_e32 v45, v45
	v_pk_add_f32 v[48:49], v[48:49], 1.0 op_sel_hi:[1,0]
	v_exp_f32_e64 v46, -v36
	v_rcp_f32_e32 v48, v48
	v_rcp_f32_e32 v49, v49
	v_exp_f32_e64 v47, -v37
	v_pk_mul_f32 v[42:43], v[44:45], v[42:43]
	v_exp_f32_e64 v44, -v38
	v_exp_f32_e64 v45, -v39
	v_pk_mul_f32 v[40:41], v[48:49], v[40:41]
	v_pk_mul_f32 v[34:35], v[38:39], v[34:35]
	v_cvt_pk_bf16_f32 v40, v40, v41
	v_cvt_pk_bf16_f32 v41, v42, v43
	v_pk_add_f32 v[42:43], v[46:47], 1.0 op_sel_hi:[1,0]
	v_pk_add_f32 v[38:39], v[44:45], 1.0 op_sel_hi:[1,0]
	v_rcp_f32_e32 v42, v42
	v_rcp_f32_e32 v43, v43
	v_rcp_f32_e32 v38, v38
	v_rcp_f32_e32 v39, v39
	v_pk_mul_f32 v[32:33], v[36:37], v[32:33]
	v_exp_f32_e64 v36, -v30
	v_pk_mul_f32 v[32:33], v[42:43], v[32:33]
	v_exp_f32_e64 v37, -v31
	v_cvt_pk_bf16_f32 v42, v32, v33
	v_pk_mul_f32 v[32:33], v[38:39], v[34:35]
	v_pk_mul_f32 v[24:25], v[28:29], v[24:25]
	v_cvt_pk_bf16_f32 v43, v32, v33
	v_exp_f32_e64 v32, -v28
	v_exp_f32_e64 v33, -v29
	v_pk_add_f32 v[28:29], v[36:37], 1.0 op_sel_hi:[1,0]
	v_pk_mul_f32 v[26:27], v[30:31], v[26:27]
	v_rcp_f32_e32 v28, v28
	v_rcp_f32_e32 v29, v29
	v_pk_add_f32 v[32:33], v[32:33], 1.0 op_sel_hi:[1,0]
	v_exp_f32_e64 v30, -v20
	v_rcp_f32_e32 v32, v32
	v_rcp_f32_e32 v33, v33
	v_exp_f32_e64 v31, -v21
	v_pk_mul_f32 v[26:27], v[28:29], v[26:27]
	v_exp_f32_e64 v28, -v22
	v_exp_f32_e64 v29, -v23
	v_pk_mul_f32 v[24:25], v[32:33], v[24:25]
	v_pk_mul_f32 v[18:19], v[22:23], v[18:19]
	v_cvt_pk_bf16_f32 v24, v24, v25
	v_cvt_pk_bf16_f32 v25, v26, v27
	v_pk_add_f32 v[26:27], v[30:31], 1.0 op_sel_hi:[1,0]
	v_pk_add_f32 v[22:23], v[28:29], 1.0 op_sel_hi:[1,0]
	v_rcp_f32_e32 v26, v26
	v_rcp_f32_e32 v27, v27
	v_rcp_f32_e32 v22, v22
	v_rcp_f32_e32 v23, v23
	v_pk_mul_f32 v[16:17], v[20:21], v[16:17]
	v_exp_f32_e64 v20, -v14
	v_pk_mul_f32 v[16:17], v[26:27], v[16:17]
	v_exp_f32_e64 v21, -v15
	v_cvt_pk_bf16_f32 v26, v16, v17
	v_pk_mul_f32 v[16:17], v[22:23], v[18:19]
	v_pk_mul_f32 v[8:9], v[12:13], v[8:9]
	v_cvt_pk_bf16_f32 v27, v16, v17
	v_exp_f32_e64 v16, -v12
	v_exp_f32_e64 v17, -v13
	v_pk_add_f32 v[12:13], v[20:21], 1.0 op_sel_hi:[1,0]
	v_pk_mul_f32 v[10:11], v[14:15], v[10:11]
	v_rcp_f32_e32 v12, v12
	v_rcp_f32_e32 v13, v13
	v_pk_add_f32 v[16:17], v[16:17], 1.0 op_sel_hi:[1,0]
	v_exp_f32_e64 v14, -v4
	v_rcp_f32_e32 v16, v16
	v_rcp_f32_e32 v17, v17
	v_exp_f32_e64 v15, -v5
	v_pk_mul_f32 v[10:11], v[12:13], v[10:11]
	v_exp_f32_e64 v12, -v6
	v_exp_f32_e64 v13, -v7
	v_pk_mul_f32 v[8:9], v[16:17], v[8:9]
	v_pk_mul_f32 v[2:3], v[6:7], v[2:3]
	v_cvt_pk_bf16_f32 v8, v8, v9
	v_cvt_pk_bf16_f32 v9, v10, v11
	v_pk_add_f32 v[10:11], v[14:15], 1.0 op_sel_hi:[1,0]
	v_pk_add_f32 v[6:7], v[12:13], 1.0 op_sel_hi:[1,0]
	v_rcp_f32_e32 v10, v10
	v_rcp_f32_e32 v11, v11
	v_mov_b32_e32 v144, v147
	v_mov_b32_e32 v145, v146
	s_lshl_b32 s19, s62, 7
	v_rcp_f32_e32 v6, v6
	v_rcp_f32_e32 v7, v7
	s_lshl_b32 s17, s40, 8
	s_or_b32 s19, s19, s48
	v_lshl_add_u32 v144, v144, 3, s19
	s_add_i32 s17, s17, s47
	v_pk_mul_f32 v[0:1], v[4:5], v[0:1]
	v_add_u32_e32 v152, s17, v145
	v_ashrrev_i32_e32 v145, 31, v144
	v_pk_mul_f32 v[0:1], v[10:11], v[0:1]
	v_lshl_add_u64 v[144:145], v[144:145], 1, s[22:23]
	v_add_u32_e32 v114, 16, v152
	v_add_u32_e32 v98, 32, v152
	v_add_u32_e32 v82, 48, v152
	v_add_u32_e32 v66, 0x80, v152
	v_add_u32_e32 v50, 0x90, v152
	v_add_u32_e32 v34, 0xa0, v152
	v_add_u32_e32 v18, 0xb0, v152
	v_cvt_pk_bf16_f32 v10, v0, v1
	v_pk_mul_f32 v[0:1], v[6:7], v[2:3]
	v_mad_i64_i32 v[156:157], s[42:43], v152, s61, v[144:145]
	v_mad_i64_i32 v[114:115], s[42:43], v114, s61, v[144:145]
	v_mad_i64_i32 v[98:99], s[42:43], v98, s61, v[144:145]
	v_mad_i64_i32 v[82:83], s[42:43], v82, s61, v[144:145]
	v_mad_i64_i32 v[66:67], s[42:43], v66, s61, v[144:145]
	v_mad_i64_i32 v[50:51], s[42:43], v50, s61, v[144:145]
	v_mad_i64_i32 v[34:35], s[42:43], v34, s61, v[144:145]
	v_mad_i64_i32 v[18:19], s[42:43], v18, s61, v[144:145]
	v_cvt_pk_bf16_f32 v11, v0, v1
	s_andn2_b64 vcc, exec, s[0:1]
	s_mov_b64 s[0:1], -1
	global_store_dwordx4 v[156:157], v[120:123], off nt
	global_store_dwordx4 v[114:115], v[104:107], off nt
	global_store_dwordx4 v[98:99], v[88:91], off nt
	global_store_dwordx4 v[82:83], v[72:75], off nt
	global_store_dwordx4 v[66:67], v[56:59], off nt
	global_store_dwordx4 v[50:51], v[40:43], off nt
	global_store_dwordx4 v[34:35], v[24:27], off nt
	global_store_dwordx4 v[18:19], v[8:11], off nt
	s_cbranch_vccnz .LBB0_272
	s_andn2_b64 vcc, exec, s[10:11]
	s_cbranch_vccnz .LBB0_271
	s_barrier
	s_branch .LBB0_271

; __device__ __forceinline__ unsigned cvt_pk_bf16(float lo, float hi) { f32x2c_t v = {lo, hi}; bf16x2c_t b = __builtin_convertvector(v, bf16x2c_t); return __builtin_bit_cast(unsigned, b); }
; __device__ __forceinline__ f32x4 bf4_lo(u32x4 w) { return (f32x4){__uint_as_float(w.x << 16), __uint_as_float(w.x & 0xffff0000u), __uint_as_float(w.y << 16), __uint_as_float(w.y & 0xffff0000u)}; }
;     __device__ __forceinline__ void operator()(const f32x4 (&acc)[2][2][4][2], const Unit& u, int wr, int wc, int fr, int fq) const {
;     ...
;         const int row0 = u.pm * BM + wr * 64 + fr, col0 = u.pn * BM + wc * 32 + 8 * fq, b = u.pm >> 4;
;         f32x4 gv[2][2];
; #pragma unroll
;         for (int bj = 0; bj < 2; ++bj)
; #pragma unroll
;             for (int n = 0; n < 2; ++n) gv[bj][n] = *(const f32x4*)(gate + (size_t)b * NMODC + col0 + bj * HALF + n * 4) * (MIX ? 1.0f : 0.5f);
;         u32x4 xw[2][4][2];
;         if constexpr (!XF32) {
; #pragma unroll
;             for (int ai = 0; ai < 2; ++ai)
; #pragma unroll
;                 for (int m = 0; m < 4; ++m)
; #pragma unroll
;                     for (int bj = 0; bj < 2; ++bj) xw[ai][m][bj] = *(const u32x4*)((const bf16_t*)xin + (size_t)(row0 + ai * HALF + m * 16) * 1024 + col0 + bj * HALF);
;         }
; #pragma unroll
;         for (int ai = 0; ai < 2; ++ai)
; #pragma unroll
;             for (int m = 0; m < 4; ++m) { const int row = row0 + ai * HALF + m * 16; const size_t off = (size_t)row * 1024 + col0; float rs = 1.f; if constexpr (MIX) { const float* sp = rs2 + 4 * row + 2; rs = 1.0f / sqrtf((sp[0] + sp[1]) * (1.f / 512.f) + NEPS); }
; #pragma unroll
;                 for (int bj = 0; bj < 2; ++bj) { f32x4 x0, x1;
;                     if constexpr (XF32) { x0 = *(const f32x4*)((const float*)xin + off + bj * HALF); x1 = *(const f32x4*)((const float*)xin + off + bj * HALF + 4); }
;                     else { const u32x4 w = xw[ai][m][bj]; x0 = bf4_lo(w); x1 = bf4_hi(w); }
;                     const f32x4 o0 = x0 + gv[bj][0] * (acc[ai][bj][m][0] * rs), o1 = x1 + gv[bj][1] * (acc[ai][bj][m][1] * rs);
;                     u32x4 w; w.x = cvt_pk_bf16(o0[0], o0[1]); w.y = cvt_pk_bf16(o0[2], o0[3]); w.z = cvt_pk_bf16(o1[0], o1[1]); w.w = cvt_pk_bf16(o1[2], o1[3]);
;                     *(u32x4*)(xout + off + bj * HALF) = w; } }
.LBB0_359:
	s_lshl_b32 s38, s61, 8
	v_mov_b32_e32 v144, v155
	v_mov_b32_e32 v152, v154
	s_add_i32 s40, s38, s47
	s_lshl_b32 s38, s62, 8
	s_or_b32 s38, s38, s48
	v_lshl_add_u32 v144, v144, 3, s38
	s_ashr_i32 s38, s61, 4
	s_mul_hi_i32 s39, s38, 0x9000
	s_mul_i32 s38, s38, 0x9000
	s_add_u32 s38, s37, s38
	s_addc_u32 s39, s46, s39
	v_ashrrev_i32_e32 v145, 31, v144
	v_add_u32_e32 v152, s40, v152
	v_lshl_add_u64 v[150:151], v[144:145], 2, s[38:39]
	v_ashrrev_i32_e32 v153, 31, v152
	global_load_dwordx4 v[160:163], v[150:151], off offset:16
	global_load_dwordx4 v[146:149], v[150:151], off
	v_lshlrev_b64 v[152:153], 10, v[152:153]
	v_lshl_add_u64 v[152:153], v[152:153], 0, v[144:145]
	v_lshl_add_u64 v[180:181], v[152:153], 2, s[52:53]
	global_load_dwordx4 v[172:175], v[150:151], off offset:528
	global_load_dwordx4 v[176:179], v[150:151], off offset:512
	s_and_b64 vcc, exec, s[0:1]
	s_mov_b64 s[0:1], -1
	v_lshl_add_u64 v[228:229], v[152:153], 2, s[52:53]
	s_mov_b64 s[38:39], 0x4000
	v_lshl_add_u64 v[186:187], v[152:153], 0, s[38:39]
	v_lshl_add_u64 v[230:231], v[186:187], 2, s[52:53]
	s_mov_b64 s[38:39], 0x8000
	v_lshl_add_u64 v[186:187], v[152:153], 0, s[38:39]
	v_lshl_add_u64 v[232:233], v[186:187], 2, s[52:53]
	s_mov_b64 s[38:39], 0xc000
	v_lshl_add_u64 v[186:187], v[152:153], 0, s[38:39]
	v_lshl_add_u64 v[234:235], v[186:187], 2, s[52:53]
	s_mov_b64 s[38:39], 0x20000
	v_lshl_add_u64 v[186:187], v[152:153], 0, s[38:39]
	v_lshl_add_u64 v[236:237], v[186:187], 2, s[52:53]
	s_mov_b64 s[38:39], 0x24000
	v_lshl_add_u64 v[186:187], v[152:153], 0, s[38:39]
	v_lshl_add_u64 v[238:239], v[186:187], 2, s[52:53]
	s_mov_b64 s[38:39], 0x28000
	v_lshl_add_u64 v[186:187], v[152:153], 0, s[38:39]
	v_lshl_add_u64 v[240:241], v[186:187], 2, s[52:53]
	s_mov_b64 s[38:39], 0x2c000
	v_lshl_add_u64 v[186:187], v[152:153], 0, s[38:39]
	v_lshl_add_u64 v[242:243], v[186:187], 2, s[52:53]
	global_load_dword v252, v[228:229], off offset:0
	global_load_dword v252, v[228:229], off offset:512
	global_load_dword v252, v[230:231], off offset:0
	global_load_dword v252, v[230:231], off offset:512
	global_load_dword v252, v[232:233], off offset:0
	global_load_dword v252, v[232:233], off offset:512
	global_load_dword v252, v[234:235], off offset:0
	global_load_dword v252, v[234:235], off offset:512
	global_load_dword v252, v[236:237], off offset:0
	global_load_dword v252, v[236:237], off offset:512
	global_load_dword v252, v[238:239], off offset:0
	global_load_dword v252, v[238:239], off offset:512
	global_load_dword v252, v[240:241], off offset:0
	global_load_dword v252, v[240:241], off offset:512
	global_load_dword v252, v[242:243], off offset:0
	global_load_dword v252, v[242:243], off offset:512
	global_load_dwordx4 v[190:193], v[228:229], off offset:0
	global_load_dwordx4 v[194:197], v[228:229], off offset:16
	global_load_dwordx4 v[198:201], v[228:229], off offset:512
	global_load_dwordx4 v[202:205], v[228:229], off offset:528
	global_load_dwordx4 v[206:209], v[230:231], off offset:0
	global_load_dwordx4 v[210:213], v[230:231], off offset:16
	global_load_dwordx4 v[214:217], v[230:231], off offset:512
	global_load_dwordx4 v[218:221], v[230:231], off offset:528
	global_load_dwordx4 v[244:247], v[232:233], off offset:0
	global_load_dwordx4 v[248:251], v[232:233], off offset:16
	s_waitcnt vmcnt(26)
	v_pk_mul_f32 v[150:151], v[160:161], 0.5 op_sel_hi:[1,0]
	v_pk_mul_f32 v[144:145], v[148:149], 0.5 op_sel_hi:[1,0]
	v_pk_mul_f32 v[146:147], v[146:147], 0.5 op_sel_hi:[1,0]
	v_pk_mul_f32 v[148:149], v[162:163], 0.5 op_sel_hi:[1,0]
	v_pk_mul_f32 v[164:165], v[178:179], 0.5 op_sel_hi:[1,0]
	v_pk_mul_f32 v[166:167], v[176:177], 0.5 op_sel_hi:[1,0]
	v_pk_mul_f32 v[168:169], v[174:175], 0.5 op_sel_hi:[1,0]
	v_pk_mul_f32 v[170:171], v[172:173], 0.5 op_sel_hi:[1,0]
	s_waitcnt vmcnt(8)
	v_pk_fma_f32 v[126:127], v[126:127], v[144:145], v[192:193]
	v_pk_fma_f32 v[124:125], v[124:125], v[146:147], v[190:191]
	v_pk_fma_f32 v[160:161], v[122:123], v[148:149], v[196:197]
	v_pk_fma_f32 v[122:123], v[120:121], v[150:151], v[194:195]
	v_cvt_pk_bf16_f32 v120, v124, v125
	v_cvt_pk_bf16_f32 v121, v126, v127
	v_cvt_pk_bf16_f32 v122, v122, v123
	v_cvt_pk_bf16_f32 v123, v160, v161
	v_lshl_add_u64 v[182:183], v[152:153], 1, s[24:25]
	global_store_dwordx4 v[182:183], v[120:123], off
	global_load_dwordx4 v[190:193], v[232:233], off offset:512
	global_load_dwordx4 v[194:197], v[232:233], off offset:528
	s_waitcnt vmcnt(9)
	v_pk_fma_f32 v[118:119], v[118:119], v[164:165], v[200:201]
	v_pk_fma_f32 v[116:117], v[116:117], v[166:167], v[198:199]
	v_pk_fma_f32 v[160:161], v[114:115], v[168:169], v[204:205]
	v_pk_fma_f32 v[114:115], v[112:113], v[170:171], v[202:203]
	v_cvt_pk_bf16_f32 v112, v116, v117
	v_cvt_pk_bf16_f32 v113, v118, v119
	v_cvt_pk_bf16_f32 v114, v114, v115
	v_cvt_pk_bf16_f32 v115, v160, v161
	global_store_dwordx4 v[182:183], v[112:115], off offset:256
	global_load_dwordx4 v[198:201], v[234:235], off offset:0
	global_load_dwordx4 v[202:205], v[234:235], off offset:16
	s_waitcnt vmcnt(10)
	v_pk_fma_f32 v[110:111], v[110:111], v[144:145], v[208:209]
	v_pk_fma_f32 v[108:109], v[108:109], v[146:147], v[206:207]
	v_pk_fma_f32 v[160:161], v[106:107], v[148:149], v[212:213]
	v_pk_fma_f32 v[106:107], v[104:105], v[150:151], v[210:211]
	v_cvt_pk_bf16_f32 v104, v108, v109
	v_cvt_pk_bf16_f32 v105, v110, v111
	v_cvt_pk_bf16_f32 v106, v106, v107
	v_cvt_pk_bf16_f32 v107, v160, v161
	s_mov_b64 s[38:39], 0x4000
	v_lshl_add_u64 v[186:187], v[152:153], 0, s[38:39]
	v_lshl_add_u64 v[182:183], v[186:187], 1, s[24:25]
	global_store_dwordx4 v[182:183], v[104:107], off
	global_load_dwordx4 v[206:209], v[234:235], off offset:512
	global_load_dwordx4 v[210:213], v[234:235], off offset:528
	s_waitcnt vmcnt(11)
; __device__ __forceinline__ unsigned cvt_pk_bf16(float lo, float hi) { f32x2c_t v = {lo, hi}; bf16x2c_t b = __builtin_convertvector(v, bf16x2c_t); return __builtin_bit_cast(unsigned, b); }
; __device__ __forceinline__ f32x4 bf4_lo(u32x4 w) { return (f32x4){__uint_as_float(w.x << 16), __uint_as_float(w.x & 0xffff0000u), __uint_as_float(w.y << 16), __uint_as_float(w.y & 0xffff0000u)}; }
; __device__ __forceinline__ f32x4 bf4_hi(u32x4 w) { return (f32x4){__uint_as_float(w.z << 16), __uint_as_float(w.z & 0xffff0000u), __uint_as_float(w.w << 16), __uint_as_float(w.w & 0xffff0000u)}; }
;     __device__ __forceinline__ void operator()(const f32x4 (&acc)[2][2][4][2], const Unit& u, int wr, int wc, int fr, int fq) const {
;     ...
;         for (int ai = 0; ai < 2; ++ai)
; #pragma unroll
;             for (int m = 0; m < 4; ++m) { const int row = row0 + ai * HALF + m * 16; const size_t off = (size_t)row * 1024 + col0; float rs = 1.f; if constexpr (MIX) { const float* sp = rs2 + 4 * row + 2; rs = 1.0f / sqrtf((sp[0] + sp[1]) * (1.f / 512.f) + NEPS); }
; #pragma unroll
;                 for (int bj = 0; bj < 2; ++bj) { f32x4 x0, x1;
;                     if constexpr (XF32) { x0 = *(const f32x4*)((const float*)xin + off + bj * HALF); x1 = *(const f32x4*)((const float*)xin + off + bj * HALF + 4); }
;                     else { const u32x4 w = xw[ai][m][bj]; x0 = bf4_lo(w); x1 = bf4_hi(w); }
;                     const f32x4 o0 = x0 + gv[bj][0] * (acc[ai][bj][m][0] * rs), o1 = x1 + gv[bj][1] * (acc[ai][bj][m][1] * rs);
;                     u32x4 w; w.x = cvt_pk_bf16(o0[0], o0[1]); w.y = cvt_pk_bf16(o0[2], o0[3]); w.z = cvt_pk_bf16(o1[0], o1[1]); w.w = cvt_pk_bf16(o1[2], o1[3]);
;                     *(u32x4*)(xout + off + bj * HALF) = w; } }
	v_pk_fma_f32 v[102:103], v[102:103], v[164:165], v[216:217]
	v_pk_fma_f32 v[100:101], v[100:101], v[166:167], v[214:215]
	v_pk_fma_f32 v[160:161], v[98:99], v[168:169], v[220:221]
	v_pk_fma_f32 v[98:99], v[96:97], v[170:171], v[218:219]
	v_cvt_pk_bf16_f32 v96, v100, v101
	v_cvt_pk_bf16_f32 v97, v102, v103
	v_cvt_pk_bf16_f32 v98, v98, v99
	v_cvt_pk_bf16_f32 v99, v160, v161
	global_store_dwordx4 v[182:183], v[96:99], off offset:256
	global_load_dwordx4 v[214:217], v[236:237], off offset:0
	global_load_dwordx4 v[218:221], v[236:237], off offset:16
	s_waitcnt vmcnt(12)
	v_pk_fma_f32 v[94:95], v[94:95], v[144:145], v[246:247]
	v_pk_fma_f32 v[92:93], v[92:93], v[146:147], v[244:245]
	v_pk_fma_f32 v[160:161], v[90:91], v[148:149], v[250:251]
	v_pk_fma_f32 v[90:91], v[88:89], v[150:151], v[248:249]
	v_cvt_pk_bf16_f32 v88, v92, v93
	v_cvt_pk_bf16_f32 v89, v94, v95
	v_cvt_pk_bf16_f32 v90, v90, v91
	v_cvt_pk_bf16_f32 v91, v160, v161
	s_mov_b64 s[38:39], 0x8000
	v_lshl_add_u64 v[186:187], v[152:153], 0, s[38:39]
	v_lshl_add_u64 v[182:183], v[186:187], 1, s[24:25]
	global_store_dwordx4 v[182:183], v[88:91], off
	global_load_dwordx4 v[244:247], v[236:237], off offset:512
	global_load_dwordx4 v[248:251], v[236:237], off offset:528
	s_waitcnt vmcnt(12)
	v_pk_fma_f32 v[86:87], v[86:87], v[164:165], v[192:193]
	v_pk_fma_f32 v[84:85], v[84:85], v[166:167], v[190:191]
	v_pk_fma_f32 v[160:161], v[82:83], v[168:169], v[196:197]
	v_pk_fma_f32 v[82:83], v[80:81], v[170:171], v[194:195]
	v_cvt_pk_bf16_f32 v80, v84, v85
	v_cvt_pk_bf16_f32 v81, v86, v87
	v_cvt_pk_bf16_f32 v82, v82, v83
	v_cvt_pk_bf16_f32 v83, v160, v161
	global_store_dwordx4 v[182:183], v[80:83], off offset:256
	global_load_dwordx4 v[190:193], v[238:239], off offset:0
	global_load_dwordx4 v[194:197], v[238:239], off offset:16
	s_waitcnt vmcnt(12)
	v_pk_fma_f32 v[78:79], v[78:79], v[144:145], v[200:201]
	v_pk_fma_f32 v[76:77], v[76:77], v[146:147], v[198:199]
	v_pk_fma_f32 v[160:161], v[74:75], v[148:149], v[204:205]
	v_pk_fma_f32 v[74:75], v[72:73], v[150:151], v[202:203]
	v_cvt_pk_bf16_f32 v72, v76, v77
	v_cvt_pk_bf16_f32 v73, v78, v79
	v_cvt_pk_bf16_f32 v74, v74, v75
	v_cvt_pk_bf16_f32 v75, v160, v161
	s_mov_b64 s[38:39], 0xc000
	v_lshl_add_u64 v[186:187], v[152:153], 0, s[38:39]
	v_lshl_add_u64 v[182:183], v[186:187], 1, s[24:25]
	global_store_dwordx4 v[182:183], v[72:75], off
	global_load_dwordx4 v[198:201], v[238:239], off offset:512
	global_load_dwordx4 v[202:205], v[238:239], off offset:528
	s_waitcnt vmcnt(12)
	v_pk_fma_f32 v[70:71], v[70:71], v[164:165], v[208:209]
	v_pk_fma_f32 v[68:69], v[68:69], v[166:167], v[206:207]
	v_pk_fma_f32 v[160:161], v[66:67], v[168:169], v[212:213]
	v_pk_fma_f32 v[66:67], v[64:65], v[170:171], v[210:211]
	v_cvt_pk_bf16_f32 v64, v68, v69
	v_cvt_pk_bf16_f32 v65, v70, v71
	v_cvt_pk_bf16_f32 v66, v66, v67
	v_cvt_pk_bf16_f32 v67, v160, v161
	global_store_dwordx4 v[182:183], v[64:67], off offset:256
	global_load_dwordx4 v[206:209], v[240:241], off offset:0
	global_load_dwordx4 v[210:213], v[240:241], off offset:16
	s_waitcnt vmcnt(12)
	v_pk_fma_f32 v[62:63], v[62:63], v[144:145], v[216:217]
	v_pk_fma_f32 v[60:61], v[60:61], v[146:147], v[214:215]
	v_pk_fma_f32 v[160:161], v[58:59], v[148:149], v[220:221]
	v_pk_fma_f32 v[58:59], v[56:57], v[150:151], v[218:219]
	v_cvt_pk_bf16_f32 v56, v60, v61
	v_cvt_pk_bf16_f32 v57, v62, v63
	v_cvt_pk_bf16_f32 v58, v58, v59
	v_cvt_pk_bf16_f32 v59, v160, v161
	s_mov_b64 s[38:39], 0x20000
	v_lshl_add_u64 v[186:187], v[152:153], 0, s[38:39]
	v_lshl_add_u64 v[182:183], v[186:187], 1, s[24:25]
	global_store_dwordx4 v[182:183], v[56:59], off
	global_load_dwordx4 v[214:217], v[240:241], off offset:512
	global_load_dwordx4 v[218:221], v[240:241], off offset:528
	s_waitcnt vmcnt(12)
; __device__ __forceinline__ unsigned cvt_pk_bf16(float lo, float hi) { f32x2c_t v = {lo, hi}; bf16x2c_t b = __builtin_convertvector(v, bf16x2c_t); return __builtin_bit_cast(unsigned, b); }
; __device__ __forceinline__ f32x4 bf4_lo(u32x4 w) { return (f32x4){__uint_as_float(w.x << 16), __uint_as_float(w.x & 0xffff0000u), __uint_as_float(w.y << 16), __uint_as_float(w.y & 0xffff0000u)}; }
; __device__ __forceinline__ f32x4 bf4_hi(u32x4 w) { return (f32x4){__uint_as_float(w.z << 16), __uint_as_float(w.z & 0xffff0000u), __uint_as_float(w.w << 16), __uint_as_float(w.w & 0xffff0000u)}; }
;     __device__ __forceinline__ void operator()(const f32x4 (&acc)[2][2][4][2], const Unit& u, int wr, int wc, int fr, int fq) const {
;     ...
;         for (int ai = 0; ai < 2; ++ai)
; #pragma unroll
;             for (int m = 0; m < 4; ++m) { const int row = row0 + ai * HALF + m * 16; const size_t off = (size_t)row * 1024 + col0; float rs = 1.f; if constexpr (MIX) { const float* sp = rs2 + 4 * row + 2; rs = 1.0f / sqrtf((sp[0] + sp[1]) * (1.f / 512.f) + NEPS); }
; #pragma unroll
;                 for (int bj = 0; bj < 2; ++bj) { f32x4 x0, x1;
;                     if constexpr (XF32) { x0 = *(const f32x4*)((const float*)xin + off + bj * HALF); x1 = *(const f32x4*)((const float*)xin + off + bj * HALF + 4); }
;                     else { const u32x4 w = xw[ai][m][bj]; x0 = bf4_lo(w); x1 = bf4_hi(w); }
;                     const f32x4 o0 = x0 + gv[bj][0] * (acc[ai][bj][m][0] * rs), o1 = x1 + gv[bj][1] * (acc[ai][bj][m][1] * rs);
;                     u32x4 w; w.x = cvt_pk_bf16(o0[0], o0[1]); w.y = cvt_pk_bf16(o0[2], o0[3]); w.z = cvt_pk_bf16(o1[0], o1[1]); w.w = cvt_pk_bf16(o1[2], o1[3]);
;                     *(u32x4*)(xout + off + bj * HALF) = w; } }
	v_pk_fma_f32 v[54:55], v[54:55], v[164:165], v[246:247]
	v_pk_fma_f32 v[52:53], v[52:53], v[166:167], v[244:245]
	v_pk_fma_f32 v[160:161], v[50:51], v[168:169], v[250:251]
	v_pk_fma_f32 v[50:51], v[48:49], v[170:171], v[248:249]
	v_cvt_pk_bf16_f32 v48, v52, v53
	v_cvt_pk_bf16_f32 v49, v54, v55
	v_cvt_pk_bf16_f32 v50, v50, v51
	v_cvt_pk_bf16_f32 v51, v160, v161
	global_store_dwordx4 v[182:183], v[48:51], off offset:256
	global_load_dwordx4 v[244:247], v[242:243], off offset:0
	global_load_dwordx4 v[248:251], v[242:243], off offset:16
	s_waitcnt vmcnt(12)
	v_pk_fma_f32 v[46:47], v[46:47], v[144:145], v[192:193]
	v_pk_fma_f32 v[44:45], v[44:45], v[146:147], v[190:191]
	v_pk_fma_f32 v[160:161], v[42:43], v[148:149], v[196:197]
	v_pk_fma_f32 v[42:43], v[40:41], v[150:151], v[194:195]
	v_cvt_pk_bf16_f32 v40, v44, v45
	v_cvt_pk_bf16_f32 v41, v46, v47
	v_cvt_pk_bf16_f32 v42, v42, v43
	v_cvt_pk_bf16_f32 v43, v160, v161
	s_mov_b64 s[38:39], 0x24000
	v_lshl_add_u64 v[186:187], v[152:153], 0, s[38:39]
	v_lshl_add_u64 v[182:183], v[186:187], 1, s[24:25]
	global_store_dwordx4 v[182:183], v[40:43], off
	global_load_dwordx4 v[190:193], v[242:243], off offset:512
	global_load_dwordx4 v[194:197], v[242:243], off offset:528
	s_waitcnt vmcnt(12)
	v_pk_fma_f32 v[38:39], v[38:39], v[164:165], v[200:201]
	v_pk_fma_f32 v[36:37], v[36:37], v[166:167], v[198:199]
	v_pk_fma_f32 v[160:161], v[34:35], v[168:169], v[204:205]
	v_pk_fma_f32 v[34:35], v[32:33], v[170:171], v[202:203]
	v_cvt_pk_bf16_f32 v32, v36, v37
	v_cvt_pk_bf16_f32 v33, v38, v39
	v_cvt_pk_bf16_f32 v34, v34, v35
	v_cvt_pk_bf16_f32 v35, v160, v161
	global_store_dwordx4 v[182:183], v[32:35], off offset:256
	s_waitcnt vmcnt(10)
	v_pk_fma_f32 v[30:31], v[30:31], v[144:145], v[208:209]
	v_pk_fma_f32 v[28:29], v[28:29], v[146:147], v[206:207]
	v_pk_fma_f32 v[160:161], v[26:27], v[148:149], v[212:213]
	v_pk_fma_f32 v[26:27], v[24:25], v[150:151], v[210:211]
	v_cvt_pk_bf16_f32 v24, v28, v29
	v_cvt_pk_bf16_f32 v25, v30, v31
	v_cvt_pk_bf16_f32 v26, v26, v27
	v_cvt_pk_bf16_f32 v27, v160, v161
	s_mov_b64 s[38:39], 0x28000
	v_lshl_add_u64 v[186:187], v[152:153], 0, s[38:39]
	v_lshl_add_u64 v[182:183], v[186:187], 1, s[24:25]
	global_store_dwordx4 v[182:183], v[24:27], off
	s_waitcnt vmcnt(8)
	v_pk_fma_f32 v[22:23], v[22:23], v[164:165], v[216:217]
	v_pk_fma_f32 v[20:21], v[20:21], v[166:167], v[214:215]
	v_pk_fma_f32 v[160:161], v[18:19], v[168:169], v[220:221]
	v_pk_fma_f32 v[18:19], v[16:17], v[170:171], v[218:219]
	v_cvt_pk_bf16_f32 v16, v20, v21
	v_cvt_pk_bf16_f32 v17, v22, v23
	v_cvt_pk_bf16_f32 v18, v18, v19
	v_cvt_pk_bf16_f32 v19, v160, v161
	global_store_dwordx4 v[182:183], v[16:19], off offset:256
	s_waitcnt vmcnt(6)
	v_pk_fma_f32 v[14:15], v[14:15], v[144:145], v[246:247]
	v_pk_fma_f32 v[12:13], v[12:13], v[146:147], v[244:245]
	v_pk_fma_f32 v[160:161], v[10:11], v[148:149], v[250:251]
	v_pk_fma_f32 v[10:11], v[8:9], v[150:151], v[248:249]
	v_cvt_pk_bf16_f32 v8, v12, v13
	v_cvt_pk_bf16_f32 v9, v14, v15
	v_cvt_pk_bf16_f32 v10, v10, v11
	v_cvt_pk_bf16_f32 v11, v160, v161
	s_mov_b64 s[38:39], 0x2c000
	v_lshl_add_u64 v[186:187], v[152:153], 0, s[38:39]
	v_lshl_add_u64 v[182:183], v[186:187], 1, s[24:25]
	global_store_dwordx4 v[182:183], v[8:11], off
	s_waitcnt vmcnt(4)
	v_pk_fma_f32 v[6:7], v[6:7], v[164:165], v[192:193]
	v_pk_fma_f32 v[4:5], v[4:5], v[166:167], v[190:191]
	v_pk_fma_f32 v[160:161], v[2:3], v[168:169], v[196:197]
	v_pk_fma_f32 v[2:3], v[0:1], v[170:171], v[194:195]
	v_cvt_pk_bf16_f32 v0, v4, v5
	v_cvt_pk_bf16_f32 v1, v6, v7
	v_cvt_pk_bf16_f32 v2, v2, v3
	v_cvt_pk_bf16_f32 v3, v160, v161
	global_store_dwordx4 v[182:183], v[0:3], off offset:256
	s_cbranch_vccnz .LBB0_344
	s_andn2_b64 vcc, exec, s[10:11]
	s_cbranch_vccnz .LBB0_343
	s_barrier
	s_branch .LBB0_343
